# v40 + GEMM K-loops: SA(0,0) stage moved from the 6-DMA phase 2 into phase 3 (DMA issue 2/4/4/6 instead of 2/6/2/6), phase-2 wait vmcnt(6)
# speedup vs baseline: 1.0064x; 1.0064x over previous
; #define PG8_STAGE(bufoff, gbase, voff) do { _Pragma("unroll") for (int _i = 0; _i < 2; ++_i) \
;         __builtin_amdgcn_global_load_lds((const unsigned*)((const char*)(gbase) + (voff)[_i]), (LAS unsigned*)(lds + (bufoff) + ldsw + _i * 8192), 16, 0, 0); } while (0)
; #define PG8_LDA(dst, b, h) do { _Pragma("unroll") for (int m = 0; m < 4; ++m) _Pragma("unroll") for (int k = 0; k < 2; ++k) dst[m][k] = *(const LAS bf16x8*)(lds + PG8_SA(b, h) + aoff + m * 2048 + k * 1024); } while (0)
; #define PG8_LDB(dst, b, h) do { _Pragma("unroll") for (int n = 0; n < 2; ++n) _Pragma("unroll") for (int k = 0; k < 2; ++k) dst[n][k] = *(const LAS bf16x8*)(lds + PG8_SB(b, h) + boff + n * 2048 + k * 1024); } while (0)
; #define PG8_MMA(ai, bj, At, Bt) do { __builtin_amdgcn_s_setprio(1); _Pragma("unroll") for (int m = 0; m < 4; ++m) _Pragma("unroll") for (int n = 0; n < 2; ++n) _Pragma("unroll") for (int k = 0; k < 2; ++k) \
;         acc[ai][bj][m][n] = __builtin_amdgcn_mfma_f32_16x16x32_bf16(Bt[n][k], At[m][k], acc[ai][bj][m][n], 0, 0, 0); __builtin_amdgcn_s_setprio(0); } while (0)
; #define PG8_WAIT_V(n) asm volatile("s_waitcnt vmcnt(" #n ")" ::: "memory")
; #define PG8_WAIT_L(n) asm volatile("s_waitcnt lgkmcnt(" #n ")" ::: "memory")
; #define PG8_BAR __builtin_amdgcn_s_barrier()
; #define PG8_SCHED __builtin_amdgcn_sched_barrier(0)
; template <class Epi, class Sched, bool ALIGN_EPI>
; DI void gemm_phase(LAS unsigned char* lds, const Gemm g, const Sched& S, const Epi& E) {
;     ...
;             PG8_LDB(B0, 0, 0); PG8_LDB(B1, 0, 1); PG8_SCHED; PG8_LDA(At, 0, 0); PG8_STAGE(PG8_SA(1, 1), a1 + hstep, voffA);
;             PG8_WAIT_V(8); PG8_WAIT_L(0); PG8_BAR; PG8_MMA(0, 0, At, B0); PG8_MMA(0, 1, At, B1); PG8_BAR; PG8_SCHED;
;             PG8_LDA(At, 0, 1); PG8_STAGE(PG8_SB(0, 0), b2, voffA); PG8_STAGE(PG8_SB(0, 1), b2 + hstep, voffA); PG8_STAGE(PG8_SA(0, 0), a2, voffA);
;             PG8_WAIT_V(8); PG8_WAIT_L(0); PG8_BAR; PG8_MMA(1, 0, At, B0); PG8_MMA(1, 1, At, B1); PG8_BAR; PG8_SCHED;
.LBB0_104:
	ds_read_b128 v[48:51], v196
	ds_read_b128 v[52:55], v196 offset:1024
	ds_read_b128 v[56:59], v196 offset:2048
	ds_read_b128 v[60:63], v196 offset:3072
	ds_read_b128 v[182:185], v197
	ds_read_b128 v[186:189], v197 offset:1024
	ds_read_b128 v[200:203], v197 offset:2048
	ds_read_b128 v[204:207], v197 offset:3072
	s_add_u32 s8, s0, 0xfffc0080
	s_addc_u32 s9, s1, -1
	s_cmp_eq_u32 s47, 12
	s_cselect_b32 s45, s7, s9
	s_cselect_b32 s44, s11, s8
	s_cselect_b32 s9, s18, s46
	s_cselect_b32 s8, s29, s31
	v_lshl_add_u64 v[224:225], s[0:1], 0, v[174:175]
	s_add_i32 m0, s64, 0xc000
	ds_read_b128 v[208:211], v194
	ds_read_b128 v[212:215], v194 offset:1024
	ds_read_b128 v[216:219], v194 offset:2048
	ds_read_b128 v[220:223], v194 offset:3072
	ds_read_b128 v[228:231], v194 offset:4096
	ds_read_b128 v[232:235], v194 offset:5120
	ds_read_b128 v[236:239], v194 offset:6144
	ds_read_b128 v[240:243], v194 offset:7168
	global_load_lds_dwordx4 v[224:225], off
	v_lshl_add_u64 v[224:225], s[0:1], 0, v[176:177]
	s_add_i32 m0, s64, 0xe000
	s_nop 0
	global_load_lds_dwordx4 v[224:225], off
	s_waitcnt vmcnt(8)
	s_waitcnt lgkmcnt(0)
	s_barrier
	s_setprio 1
	s_waitcnt lgkmcnt(0)
	v_mfma_f32_16x16x32_bf16 v[140:143], v[48:51], v[208:211], v[140:143]
	v_mfma_f32_16x16x32_bf16 v[136:139], v[56:59], v[208:211], v[136:139]
	v_mfma_f32_16x16x32_bf16 v[124:127], v[48:51], v[216:219], v[124:127]
	v_mfma_f32_16x16x32_bf16 v[120:123], v[56:59], v[216:219], v[120:123]
	v_mfma_f32_16x16x32_bf16 v[108:111], v[48:51], v[228:231], v[108:111]
	v_mfma_f32_16x16x32_bf16 v[104:107], v[56:59], v[228:231], v[104:107]
	v_mfma_f32_16x16x32_bf16 v[92:95], v[48:51], v[236:239], v[92:95]
	v_mfma_f32_16x16x32_bf16 v[88:91], v[56:59], v[236:239], v[88:91]
	v_mfma_f32_16x16x32_bf16 v[140:143], v[52:55], v[212:215], v[140:143]
	v_mfma_f32_16x16x32_bf16 v[136:139], v[60:63], v[212:215], v[136:139]
	v_mfma_f32_16x16x32_bf16 v[124:127], v[52:55], v[220:223], v[124:127]
	v_mfma_f32_16x16x32_bf16 v[120:123], v[60:63], v[220:223], v[120:123]
	v_mfma_f32_16x16x32_bf16 v[108:111], v[52:55], v[232:235], v[108:111]
	v_mfma_f32_16x16x32_bf16 v[104:107], v[60:63], v[232:235], v[104:107]
	v_mfma_f32_16x16x32_bf16 v[92:95], v[52:55], v[240:243], v[92:95]
	v_mfma_f32_16x16x32_bf16 v[88:91], v[60:63], v[240:243], v[88:91]
	s_setprio 0
	s_setprio 1
	v_mfma_f32_16x16x32_bf16 v[132:135], v[182:185], v[208:211], v[132:135]
	v_mfma_f32_16x16x32_bf16 v[128:131], v[200:203], v[208:211], v[128:131]
	v_mfma_f32_16x16x32_bf16 v[116:119], v[182:185], v[216:219], v[116:119]
	v_mfma_f32_16x16x32_bf16 v[112:115], v[200:203], v[216:219], v[112:115]
	v_mfma_f32_16x16x32_bf16 v[100:103], v[182:185], v[228:231], v[100:103]
	v_mfma_f32_16x16x32_bf16 v[96:99], v[200:203], v[228:231], v[96:99]
	v_mfma_f32_16x16x32_bf16 v[84:87], v[182:185], v[236:239], v[84:87]
	v_mfma_f32_16x16x32_bf16 v[80:83], v[200:203], v[236:239], v[80:83]
	v_mfma_f32_16x16x32_bf16 v[132:135], v[186:189], v[212:215], v[132:135]
	v_mfma_f32_16x16x32_bf16 v[128:131], v[204:207], v[212:215], v[128:131]
	v_mfma_f32_16x16x32_bf16 v[116:119], v[186:189], v[220:223], v[116:119]
	v_mfma_f32_16x16x32_bf16 v[112:115], v[204:207], v[220:223], v[112:115]
	v_mfma_f32_16x16x32_bf16 v[100:103], v[186:189], v[232:235], v[100:103]
	v_mfma_f32_16x16x32_bf16 v[96:99], v[204:207], v[232:235], v[96:99]
	v_mfma_f32_16x16x32_bf16 v[84:87], v[186:189], v[240:243], v[84:87]
	v_mfma_f32_16x16x32_bf16 v[80:83], v[204:207], v[240:243], v[80:83]
	s_setprio 0
	s_barrier
	s_add_i32 s48, s75, s63
	v_lshl_add_u64 v[224:225], s[8:9], 0, v[146:147]
	s_mov_b32 m0, s48
	ds_read_b128 v[208:211], v194 offset:16384
	ds_read_b128 v[212:215], v194 offset:17408
	ds_read_b128 v[216:219], v194 offset:18432
	ds_read_b128 v[220:223], v194 offset:19456
	ds_read_b128 v[228:231], v194 offset:20480
	ds_read_b128 v[232:235], v194 offset:21504
	ds_read_b128 v[236:239], v194 offset:22528
	ds_read_b128 v[240:243], v194 offset:23552
	global_load_lds_dwordx4 v[224:225], off
	s_add_i32 m0, s48, 0x2000
	s_add_u32 s48, s8, 0x40000
	v_lshl_add_u64 v[244:245], s[8:9], 0, v[148:149]
	s_addc_u32 s49, s9, 0
	s_add_i32 s50, s76, s63
	global_load_lds_dwordx4 v[244:245], off
	v_lshl_add_u64 v[246:247], s[48:49], 0, v[146:147]
	s_mov_b32 m0, s50
	v_lshl_add_u64 v[248:249], s[44:45], 0, v[148:149]
	global_load_lds_dwordx4 v[246:247], off
	v_lshl_add_u64 v[246:247], s[48:49], 0, v[148:149]
	s_add_i32 m0, s50, 0x2000
	s_nop 0
	global_load_lds_dwordx4 v[246:247], off
	s_waitcnt vmcnt(6)
	s_waitcnt lgkmcnt(0)
	s_barrier
	s_setprio 1
	s_waitcnt lgkmcnt(0)
	v_mfma_f32_16x16x32_bf16 v[76:79], v[48:51], v[208:211], v[76:79]
	v_mfma_f32_16x16x32_bf16 v[72:75], v[56:59], v[208:211], v[72:75]
	v_mfma_f32_16x16x32_bf16 v[44:47], v[48:51], v[216:219], v[44:47]
	v_mfma_f32_16x16x32_bf16 v[40:43], v[56:59], v[216:219], v[40:43]
	v_mfma_f32_16x16x32_bf16 v[28:31], v[48:51], v[228:231], v[28:31]
	v_mfma_f32_16x16x32_bf16 v[24:27], v[56:59], v[228:231], v[24:27]
	v_mfma_f32_16x16x32_bf16 v[12:15], v[48:51], v[236:239], v[12:15]
	v_mfma_f32_16x16x32_bf16 v[8:11], v[56:59], v[236:239], v[8:11]
	v_mfma_f32_16x16x32_bf16 v[76:79], v[52:55], v[212:215], v[76:79]
	v_mfma_f32_16x16x32_bf16 v[72:75], v[60:63], v[212:215], v[72:75]
	v_mfma_f32_16x16x32_bf16 v[44:47], v[52:55], v[220:223], v[44:47]
	v_mfma_f32_16x16x32_bf16 v[40:43], v[60:63], v[220:223], v[40:43]
	v_mfma_f32_16x16x32_bf16 v[28:31], v[52:55], v[232:235], v[28:31]
	v_mfma_f32_16x16x32_bf16 v[24:27], v[60:63], v[232:235], v[24:27]
	v_mfma_f32_16x16x32_bf16 v[12:15], v[52:55], v[240:243], v[12:15]
	v_mfma_f32_16x16x32_bf16 v[8:11], v[60:63], v[240:243], v[8:11]
	s_setprio 0
	s_setprio 1
	v_mfma_f32_16x16x32_bf16 v[36:39], v[182:185], v[216:219], v[36:39]
	v_mfma_f32_16x16x32_bf16 v[32:35], v[200:203], v[216:219], v[32:35]
	v_mfma_f32_16x16x32_bf16 v[20:23], v[182:185], v[228:231], v[20:23]
	v_mfma_f32_16x16x32_bf16 v[16:19], v[200:203], v[228:231], v[16:19]
	v_mfma_f32_16x16x32_bf16 v[4:7], v[182:185], v[236:239], v[4:7]
	v_mfma_f32_16x16x32_bf16 v[0:3], v[200:203], v[236:239], v[0:3]
	v_mfma_f32_16x16x32_bf16 v[48:51], v[182:185], v[208:211], v[68:71]
	v_mfma_f32_16x16x32_bf16 v[52:55], v[200:203], v[208:211], v[64:67]
	v_mfma_f32_16x16x32_bf16 v[36:39], v[186:189], v[220:223], v[36:39]
	v_mfma_f32_16x16x32_bf16 v[32:35], v[204:207], v[220:223], v[32:35]
	v_mfma_f32_16x16x32_bf16 v[20:23], v[186:189], v[232:235], v[20:23]
	v_mfma_f32_16x16x32_bf16 v[16:19], v[204:207], v[232:235], v[16:19]
	v_mfma_f32_16x16x32_bf16 v[4:7], v[186:189], v[240:243], v[4:7]
	v_mfma_f32_16x16x32_bf16 v[0:3], v[204:207], v[240:243], v[0:3]
	v_mfma_f32_16x16x32_bf16 v[48:51], v[186:189], v[212:215], v[48:51]
	v_mfma_f32_16x16x32_bf16 v[52:55], v[204:207], v[212:215], v[52:55]
	s_setprio 0
	s_barrier
; #define PG8_STAGE(bufoff, gbase, voff) do { _Pragma("unroll") for (int _i = 0; _i < 2; ++_i) \
;         __builtin_amdgcn_global_load_lds((const unsigned*)((const char*)(gbase) + (voff)[_i]), (LAS unsigned*)(lds + (bufoff) + ldsw + _i * 8192), 16, 0, 0); } while (0)
; #define PG8_LDA(dst, b, h) do { _Pragma("unroll") for (int m = 0; m < 4; ++m) _Pragma("unroll") for (int k = 0; k < 2; ++k) dst[m][k] = *(const LAS bf16x8*)(lds + PG8_SA(b, h) + aoff + m * 2048 + k * 1024); } while (0)
; #define PG8_LDB(dst, b, h) do { _Pragma("unroll") for (int n = 0; n < 2; ++n) _Pragma("unroll") for (int k = 0; k < 2; ++k) dst[n][k] = *(const LAS bf16x8*)(lds + PG8_SB(b, h) + boff + n * 2048 + k * 1024); } while (0)
; #define PG8_MMA(ai, bj, At, Bt) do { __builtin_amdgcn_s_setprio(1); _Pragma("unroll") for (int m = 0; m < 4; ++m) _Pragma("unroll") for (int n = 0; n < 2; ++n) _Pragma("unroll") for (int k = 0; k < 2; ++k) \
;         acc[ai][bj][m][n] = __builtin_amdgcn_mfma_f32_16x16x32_bf16(Bt[n][k], At[m][k], acc[ai][bj][m][n], 0, 0, 0); __builtin_amdgcn_s_setprio(0); } while (0)
; #define PG8_WAIT_V(n) asm volatile("s_waitcnt vmcnt(" #n ")" ::: "memory")
; #define PG8_WAIT_L(n) asm volatile("s_waitcnt lgkmcnt(" #n ")" ::: "memory")
; #define PG8_BAR __builtin_amdgcn_s_barrier()
; #define PG8_SCHED __builtin_amdgcn_sched_barrier(0)
; template <class Epi, class Sched, bool ALIGN_EPI>
; DI void gemm_phase(LAS unsigned char* lds, const Gemm g, const Sched& S, const Epi& E) {
;     ...
;             PG8_LDB(B0, 1, 0); PG8_LDB(B1, 1, 1); PG8_SCHED; PG8_LDA(At, 1, 0); PG8_STAGE(PG8_SA(0, 1), a2 + hstep, voffA);
;             PG8_WAIT_V(8); PG8_WAIT_L(0); PG8_BAR; PG8_MMA(0, 0, At, B0); PG8_MMA(0, 1, At, B1); PG8_BAR; PG8_SCHED;
	s_add_i32 s48, 0, 0x18000
	s_add_i32 s49, 0, 0x1c000
	v_add_u32_e32 v68, s48, v157
	v_add_u32_e32 v150, s49, v157
	ds_read_b128 v[56:59], v68
	ds_read_b128 v[60:63], v68 offset:1024
	ds_read_b128 v[64:67], v68 offset:2048
	ds_read_b128 v[68:71], v68 offset:3072
	ds_read_b128 v[182:185], v150
	ds_read_b128 v[186:189], v150 offset:1024
	ds_read_b128 v[200:203], v150 offset:2048
	ds_read_b128 v[204:207], v150 offset:3072
	v_lshl_add_u64 v[246:247], s[44:45], 0, v[146:147]
	s_mov_b32 m0, s64
	s_nop 0
	global_load_lds_dwordx4 v[246:247], off
	s_mov_b32 m0, s65
	s_nop 0
	global_load_lds_dwordx4 v[248:249], off
	s_add_u32 s44, s44, 0x40000
	s_addc_u32 s45, s45, 0
	s_mov_b32 m0, s66
	v_lshl_add_u64 v[250:251], s[44:45], 0, v[146:147]
	ds_read_b128 v[208:211], v194 offset:32768
	ds_read_b128 v[212:215], v194 offset:33792
	ds_read_b128 v[216:219], v194 offset:34816
	ds_read_b128 v[220:223], v194 offset:35840
	ds_read_b128 v[228:231], v194 offset:36864
	ds_read_b128 v[232:235], v194 offset:37888
	ds_read_b128 v[236:239], v194 offset:38912
	ds_read_b128 v[240:243], v194 offset:39936
	global_load_lds_dwordx4 v[250:251], off
	v_lshl_add_u64 v[250:251], s[44:45], 0, v[148:149]
	s_mov_b32 m0, s67
	s_nop 0
	global_load_lds_dwordx4 v[250:251], off
	s_waitcnt vmcnt(8)
	s_waitcnt lgkmcnt(0)
	s_barrier
	s_setprio 1
	s_waitcnt lgkmcnt(0)
	v_mfma_f32_16x16x32_bf16 v[140:143], v[56:59], v[208:211], v[140:143]
	v_mfma_f32_16x16x32_bf16 v[136:139], v[64:67], v[208:211], v[136:139]
	v_mfma_f32_16x16x32_bf16 v[124:127], v[56:59], v[216:219], v[124:127]
	v_mfma_f32_16x16x32_bf16 v[120:123], v[64:67], v[216:219], v[120:123]
	v_mfma_f32_16x16x32_bf16 v[108:111], v[56:59], v[228:231], v[108:111]
	v_mfma_f32_16x16x32_bf16 v[104:107], v[64:67], v[228:231], v[104:107]
	v_mfma_f32_16x16x32_bf16 v[92:95], v[56:59], v[236:239], v[92:95]
	v_mfma_f32_16x16x32_bf16 v[88:91], v[64:67], v[236:239], v[88:91]
	v_mfma_f32_16x16x32_bf16 v[140:143], v[60:63], v[212:215], v[140:143]
	v_mfma_f32_16x16x32_bf16 v[136:139], v[68:71], v[212:215], v[136:139]
	v_mfma_f32_16x16x32_bf16 v[124:127], v[60:63], v[220:223], v[124:127]
	v_mfma_f32_16x16x32_bf16 v[120:123], v[68:71], v[220:223], v[120:123]
	v_mfma_f32_16x16x32_bf16 v[108:111], v[60:63], v[232:235], v[108:111]
	v_mfma_f32_16x16x32_bf16 v[104:107], v[68:71], v[232:235], v[104:107]
	v_mfma_f32_16x16x32_bf16 v[92:95], v[60:63], v[240:243], v[92:95]
	v_mfma_f32_16x16x32_bf16 v[88:91], v[68:71], v[240:243], v[88:91]
	s_setprio 0
	s_setprio 1
	v_mfma_f32_16x16x32_bf16 v[132:135], v[182:185], v[208:211], v[132:135]
	v_mfma_f32_16x16x32_bf16 v[128:131], v[200:203], v[208:211], v[128:131]
	v_mfma_f32_16x16x32_bf16 v[116:119], v[182:185], v[216:219], v[116:119]
	v_mfma_f32_16x16x32_bf16 v[112:115], v[200:203], v[216:219], v[112:115]
	v_mfma_f32_16x16x32_bf16 v[100:103], v[182:185], v[228:231], v[100:103]
	v_mfma_f32_16x16x32_bf16 v[96:99], v[200:203], v[228:231], v[96:99]
	v_mfma_f32_16x16x32_bf16 v[84:87], v[182:185], v[236:239], v[84:87]
	v_mfma_f32_16x16x32_bf16 v[80:83], v[200:203], v[236:239], v[80:83]
	v_mfma_f32_16x16x32_bf16 v[132:135], v[186:189], v[212:215], v[132:135]
	v_mfma_f32_16x16x32_bf16 v[128:131], v[204:207], v[212:215], v[128:131]
	v_mfma_f32_16x16x32_bf16 v[116:119], v[186:189], v[220:223], v[116:119]
	v_mfma_f32_16x16x32_bf16 v[112:115], v[204:207], v[220:223], v[112:115]
	v_mfma_f32_16x16x32_bf16 v[100:103], v[186:189], v[232:235], v[100:103]
	v_mfma_f32_16x16x32_bf16 v[96:99], v[204:207], v[232:235], v[96:99]
	v_mfma_f32_16x16x32_bf16 v[84:87], v[186:189], v[240:243], v[84:87]
	v_mfma_f32_16x16x32_bf16 v[80:83], v[204:207], v[240:243], v[80:83]
	s_setprio 0
	s_barrier
; #define PG8_STAGE(bufoff, gbase, voff) do { _Pragma("unroll") for (int _i = 0; _i < 2; ++_i) \
;         __builtin_amdgcn_global_load_lds((const unsigned*)((const char*)(gbase) + (voff)[_i]), (LAS unsigned*)(lds + (bufoff) + ldsw + _i * 8192), 16, 0, 0); } while (0)
; #define PG8_LDA(dst, b, h) do { _Pragma("unroll") for (int m = 0; m < 4; ++m) _Pragma("unroll") for (int k = 0; k < 2; ++k) dst[m][k] = *(const LAS bf16x8*)(lds + PG8_SA(b, h) + aoff + m * 2048 + k * 1024); } while (0)
; #define PG8_MMA(ai, bj, At, Bt) do { __builtin_amdgcn_s_setprio(1); _Pragma("unroll") for (int m = 0; m < 4; ++m) _Pragma("unroll") for (int n = 0; n < 2; ++n) _Pragma("unroll") for (int k = 0; k < 2; ++k) \
;         acc[ai][bj][m][n] = __builtin_amdgcn_mfma_f32_16x16x32_bf16(Bt[n][k], At[m][k], acc[ai][bj][m][n], 0, 0, 0); __builtin_amdgcn_s_setprio(0); } while (0)
; #define PG8_WAIT_V(n) asm volatile("s_waitcnt vmcnt(" #n ")" ::: "memory")
; #define PG8_WAIT_L(n) asm volatile("s_waitcnt lgkmcnt(" #n ")" ::: "memory")
; #define PG8_BAR __builtin_amdgcn_s_barrier()
; #define PG8_SCHED __builtin_amdgcn_sched_barrier(0)
; template <class Epi, class Sched, bool ALIGN_EPI>
; DI void gemm_phase(LAS unsigned char* lds, const Gemm g, const Sched& S, const Epi& E) {
;     ...
;             PG8_LDA(At, 1, 1); PG8_STAGE(PG8_SB(1, 0), b3, voffA); PG8_STAGE(PG8_SB(1, 1), b3 + hstep, voffA); PG8_STAGE(PG8_SA(1, 0), a3, voffA);
;             PG8_WAIT_V(8); PG8_WAIT_L(0); PG8_BAR; PG8_MMA(1, 0, At, B0); PG8_MMA(1, 1, At, B1); PG8_BAR; PG8_SCHED;
;         }
	s_add_i32 s44, s48, s63
	v_lshl_add_u64 v[224:225], v[224:225], 0, s[22:23]
	s_mov_b32 m0, s44
	ds_read_b128 v[208:211], v194 offset:49152
	ds_read_b128 v[212:215], v194 offset:50176
	ds_read_b128 v[216:219], v194 offset:51200
	ds_read_b128 v[220:223], v194 offset:52224
	ds_read_b128 v[228:231], v194 offset:53248
	ds_read_b128 v[232:235], v194 offset:54272
	ds_read_b128 v[236:239], v194 offset:55296
	ds_read_b128 v[240:243], v194 offset:56320
	global_load_lds_dwordx4 v[224:225], off
	s_add_i32 m0, s44, 0x2000
	s_add_u32 s8, s8, 0x40080
	v_lshl_add_u64 v[224:225], v[244:245], 0, s[22:23]
	s_addc_u32 s9, s9, 0
	s_add_i32 s44, s49, s63
	global_load_lds_dwordx4 v[224:225], off
	v_lshl_add_u64 v[224:225], s[8:9], 0, v[146:147]
	s_mov_b32 m0, s44
	s_nop 0
	global_load_lds_dwordx4 v[224:225], off
	v_lshl_add_u64 v[224:225], s[8:9], 0, v[148:149]
	s_add_i32 m0, s44, 0x2000
	s_nop 0
	global_load_lds_dwordx4 v[224:225], off
	v_lshl_add_u64 v[224:225], v[246:247], 0, s[22:23]
	s_mov_b32 m0, s70
	s_nop 0
	global_load_lds_dwordx4 v[224:225], off
	v_lshl_add_u64 v[224:225], v[248:249], 0, s[22:23]
	s_mov_b32 m0, s71
	s_nop 0
	global_load_lds_dwordx4 v[224:225], off
	s_waitcnt vmcnt(8)
	s_waitcnt lgkmcnt(0)
	s_barrier
	s_setprio 1
	s_waitcnt lgkmcnt(0)
	v_mfma_f32_16x16x32_bf16 v[76:79], v[56:59], v[208:211], v[76:79]
	v_mfma_f32_16x16x32_bf16 v[72:75], v[64:67], v[208:211], v[72:75]
	v_mfma_f32_16x16x32_bf16 v[44:47], v[56:59], v[216:219], v[44:47]
	v_mfma_f32_16x16x32_bf16 v[40:43], v[64:67], v[216:219], v[40:43]
	v_mfma_f32_16x16x32_bf16 v[28:31], v[56:59], v[228:231], v[28:31]
	v_mfma_f32_16x16x32_bf16 v[24:27], v[64:67], v[228:231], v[24:27]
	v_mfma_f32_16x16x32_bf16 v[12:15], v[56:59], v[236:239], v[12:15]
	v_mfma_f32_16x16x32_bf16 v[8:11], v[64:67], v[236:239], v[8:11]
	v_mfma_f32_16x16x32_bf16 v[76:79], v[60:63], v[212:215], v[76:79]
	v_mfma_f32_16x16x32_bf16 v[72:75], v[68:71], v[212:215], v[72:75]
	v_mfma_f32_16x16x32_bf16 v[44:47], v[60:63], v[220:223], v[44:47]
	v_mfma_f32_16x16x32_bf16 v[40:43], v[68:71], v[220:223], v[40:43]
	v_mfma_f32_16x16x32_bf16 v[28:31], v[60:63], v[232:235], v[28:31]
	v_mfma_f32_16x16x32_bf16 v[24:27], v[68:71], v[232:235], v[24:27]
	v_mfma_f32_16x16x32_bf16 v[12:15], v[60:63], v[240:243], v[12:15]
	v_mfma_f32_16x16x32_bf16 v[8:11], v[68:71], v[240:243], v[8:11]
	s_setprio 0
	s_setprio 1
	v_mfma_f32_16x16x32_bf16 v[48:51], v[182:185], v[208:211], v[48:51]
	v_mfma_f32_16x16x32_bf16 v[68:71], v[186:189], v[212:215], v[48:51]
	v_mfma_f32_16x16x32_bf16 v[48:51], v[200:203], v[208:211], v[52:55]
	v_mfma_f32_16x16x32_bf16 v[36:39], v[182:185], v[216:219], v[36:39]
	v_mfma_f32_16x16x32_bf16 v[32:35], v[200:203], v[216:219], v[32:35]
	v_mfma_f32_16x16x32_bf16 v[20:23], v[182:185], v[228:231], v[20:23]
	v_mfma_f32_16x16x32_bf16 v[16:19], v[200:203], v[228:231], v[16:19]
	v_mfma_f32_16x16x32_bf16 v[4:7], v[182:185], v[236:239], v[4:7]
	v_mfma_f32_16x16x32_bf16 v[0:3], v[200:203], v[236:239], v[0:3]
	v_mfma_f32_16x16x32_bf16 v[64:67], v[204:207], v[212:215], v[48:51]
	v_mfma_f32_16x16x32_bf16 v[36:39], v[186:189], v[220:223], v[36:39]
	v_mfma_f32_16x16x32_bf16 v[32:35], v[204:207], v[220:223], v[32:35]
	v_mfma_f32_16x16x32_bf16 v[20:23], v[186:189], v[232:235], v[20:23]
	v_mfma_f32_16x16x32_bf16 v[16:19], v[204:207], v[232:235], v[16:19]
	v_mfma_f32_16x16x32_bf16 v[4:7], v[186:189], v[240:243], v[4:7]
	v_mfma_f32_16x16x32_bf16 v[0:3], v[204:207], v[240:243], v[0:3]
	s_setprio 0
	s_barrier
	s_add_i32 s47, s47, 2
	s_add_u32 s0, s0, 0x100
	s_addc_u32 s1, s1, 0
	s_add_u32 s31, s31, 0x100
	s_addc_u32 s46, s46, 0
	s_cmp_gt_u32 s47, 13
	s_cbranch_scc0 .LBB0_104
	s_and_b64 vcc, exec, s[24:25]
	s_cbranch_vccz .LBB0_107
	s_barrier

; #define PG8_STAGE(bufoff, gbase, voff) do { _Pragma("unroll") for (int _i = 0; _i < 2; ++_i) \
;         __builtin_amdgcn_global_load_lds((const unsigned*)((const char*)(gbase) + (voff)[_i]), (LAS unsigned*)(lds + (bufoff) + ldsw + _i * 8192), 16, 0, 0); } while (0)
; #define PG8_LDA(dst, b, h) do { _Pragma("unroll") for (int m = 0; m < 4; ++m) _Pragma("unroll") for (int k = 0; k < 2; ++k) dst[m][k] = *(const LAS bf16x8*)(lds + PG8_SA(b, h) + aoff + m * 2048 + k * 1024); } while (0)
; #define PG8_LDB(dst, b, h) do { _Pragma("unroll") for (int n = 0; n < 2; ++n) _Pragma("unroll") for (int k = 0; k < 2; ++k) dst[n][k] = *(const LAS bf16x8*)(lds + PG8_SB(b, h) + boff + n * 2048 + k * 1024); } while (0)
; #define PG8_MMA(ai, bj, At, Bt) do { __builtin_amdgcn_s_setprio(1); _Pragma("unroll") for (int m = 0; m < 4; ++m) _Pragma("unroll") for (int n = 0; n < 2; ++n) _Pragma("unroll") for (int k = 0; k < 2; ++k) \
;         acc[ai][bj][m][n] = __builtin_amdgcn_mfma_f32_16x16x32_bf16(Bt[n][k], At[m][k], acc[ai][bj][m][n], 0, 0, 0); __builtin_amdgcn_s_setprio(0); } while (0)
; #define PG8_WAIT_V(n) asm volatile("s_waitcnt vmcnt(" #n ")" ::: "memory")
; #define PG8_WAIT_L(n) asm volatile("s_waitcnt lgkmcnt(" #n ")" ::: "memory")
; #define PG8_BAR __builtin_amdgcn_s_barrier()
; #define PG8_SCHED __builtin_amdgcn_sched_barrier(0)
; template <class Epi, class Sched, bool ALIGN_EPI>
; DI void gemm_phase(LAS unsigned char* lds, const Gemm g, const Sched& S, const Epi& E) {
;     ...
;             PG8_LDB(B0, 0, 0); PG8_LDB(B1, 0, 1); PG8_SCHED; PG8_LDA(At, 0, 0); PG8_STAGE(PG8_SA(1, 1), a1 + hstep, voffA);
;             PG8_WAIT_V(8); PG8_WAIT_L(0); PG8_BAR; PG8_MMA(0, 0, At, B0); PG8_MMA(0, 1, At, B1); PG8_BAR; PG8_SCHED;
;             PG8_LDA(At, 0, 1); PG8_STAGE(PG8_SB(0, 0), b2, voffA); PG8_STAGE(PG8_SB(0, 1), b2 + hstep, voffA); PG8_STAGE(PG8_SA(0, 0), a2, voffA);
;             PG8_WAIT_V(8); PG8_WAIT_L(0); PG8_BAR; PG8_MMA(1, 0, At, B0); PG8_MMA(1, 1, At, B1); PG8_BAR; PG8_SCHED;
.LBB0_791:
	s_add_u32 s16, s0, 0xfff50080
	s_addc_u32 s17, s1, -1
	s_add_i32 s42, 0, 0x10000
	s_cmp_eq_u32 s37, 40
	s_cselect_b32 s19, s13, s17
	s_cselect_b32 s18, s12, s16
	s_cselect_b32 s17, s5, s36
	s_cselect_b32 s16, s4, s35
	s_add_i32 s44, 0, 0x14000
	v_add_u32_e32 v140, s42, v165
	v_add_u32_e32 v156, s44, v165
	ds_read_b128 v[128:131], v140
	ds_read_b128 v[132:135], v140 offset:1024
	ds_read_b128 v[136:139], v140 offset:2048
	ds_read_b128 v[140:143], v140 offset:3072
	ds_read_b128 v[144:147], v156
	ds_read_b128 v[148:151], v156 offset:1024
	ds_read_b128 v[152:155], v156 offset:2048
	ds_read_b128 v[156:159], v156 offset:3072
	v_lshl_add_u64 v[210:211], s[0:1], 0, v[170:171]
	s_add_i32 m0, s23, 0xc000
	ds_read_b128 v[160:163], v167
	ds_read_b128 v[182:185], v167 offset:1024
	ds_read_b128 v[186:189], v167 offset:2048
	ds_read_b128 v[190:193], v167 offset:3072
	ds_read_b128 v[194:197], v167 offset:4096
	ds_read_b128 v[198:201], v167 offset:5120
	ds_read_b128 v[202:205], v167 offset:6144
	ds_read_b128 v[206:209], v167 offset:7168
	global_load_lds_dwordx4 v[210:211], off
	v_lshl_add_u64 v[210:211], s[0:1], 0, v[168:169]
	s_add_i32 m0, s23, 0xe000
	s_nop 0
	global_load_lds_dwordx4 v[210:211], off
	s_waitcnt vmcnt(8)
	s_waitcnt lgkmcnt(0)
	s_barrier
	s_setprio 1
	s_waitcnt lgkmcnt(0)
	v_mfma_f32_16x16x32_bf16 v[124:127], v[128:131], v[160:163], v[124:127]
	v_mfma_f32_16x16x32_bf16 v[120:123], v[136:139], v[160:163], v[120:123]
	v_mfma_f32_16x16x32_bf16 v[108:111], v[128:131], v[186:189], v[108:111]
	v_mfma_f32_16x16x32_bf16 v[104:107], v[136:139], v[186:189], v[104:107]
	v_mfma_f32_16x16x32_bf16 v[96:99], v[128:131], v[194:197], v[96:99]
	v_mfma_f32_16x16x32_bf16 v[88:91], v[136:139], v[194:197], v[88:91]
	v_mfma_f32_16x16x32_bf16 v[80:83], v[128:131], v[202:205], v[80:83]
	v_mfma_f32_16x16x32_bf16 v[72:75], v[136:139], v[202:205], v[72:75]
	v_mfma_f32_16x16x32_bf16 v[124:127], v[132:135], v[182:185], v[124:127]
	v_mfma_f32_16x16x32_bf16 v[120:123], v[140:143], v[182:185], v[120:123]
	v_mfma_f32_16x16x32_bf16 v[108:111], v[132:135], v[190:193], v[108:111]
	v_mfma_f32_16x16x32_bf16 v[104:107], v[140:143], v[190:193], v[104:107]
	v_mfma_f32_16x16x32_bf16 v[96:99], v[132:135], v[198:201], v[96:99]
	v_mfma_f32_16x16x32_bf16 v[88:91], v[140:143], v[198:201], v[88:91]
	v_mfma_f32_16x16x32_bf16 v[80:83], v[132:135], v[206:209], v[80:83]
	v_mfma_f32_16x16x32_bf16 v[72:75], v[140:143], v[206:209], v[72:75]
	s_setprio 0
	s_setprio 1
	v_mfma_f32_16x16x32_bf16 v[116:119], v[144:147], v[160:163], v[116:119]
	v_mfma_f32_16x16x32_bf16 v[112:115], v[152:155], v[160:163], v[112:115]
	v_mfma_f32_16x16x32_bf16 v[100:103], v[144:147], v[186:189], v[100:103]
	v_mfma_f32_16x16x32_bf16 v[92:95], v[152:155], v[186:189], v[92:95]
	v_mfma_f32_16x16x32_bf16 v[84:87], v[144:147], v[194:197], v[84:87]
	v_mfma_f32_16x16x32_bf16 v[76:79], v[152:155], v[194:197], v[76:79]
	v_mfma_f32_16x16x32_bf16 v[68:71], v[144:147], v[202:205], v[68:71]
	v_mfma_f32_16x16x32_bf16 v[64:67], v[152:155], v[202:205], v[64:67]
	v_mfma_f32_16x16x32_bf16 v[116:119], v[148:151], v[182:185], v[116:119]
	v_mfma_f32_16x16x32_bf16 v[112:115], v[156:159], v[182:185], v[112:115]
	v_mfma_f32_16x16x32_bf16 v[100:103], v[148:151], v[190:193], v[100:103]
	v_mfma_f32_16x16x32_bf16 v[92:95], v[156:159], v[190:193], v[92:95]
	v_mfma_f32_16x16x32_bf16 v[84:87], v[148:151], v[198:201], v[84:87]
	v_mfma_f32_16x16x32_bf16 v[76:79], v[156:159], v[198:201], v[76:79]
	v_mfma_f32_16x16x32_bf16 v[68:71], v[148:151], v[206:209], v[68:71]
	v_mfma_f32_16x16x32_bf16 v[64:67], v[156:159], v[206:209], v[64:67]
	s_setprio 0
	s_barrier
	s_add_i32 s42, s42, s20
	v_lshl_add_u64 v[210:211], s[16:17], 0, v[170:171]
	s_mov_b32 m0, s42
	ds_read_b128 v[160:163], v167 offset:16384
	ds_read_b128 v[182:185], v167 offset:17408
	ds_read_b128 v[186:189], v167 offset:18432
	ds_read_b128 v[190:193], v167 offset:19456
	ds_read_b128 v[194:197], v167 offset:20480
	ds_read_b128 v[198:201], v167 offset:21504
	ds_read_b128 v[202:205], v167 offset:22528
	ds_read_b128 v[206:209], v167 offset:23552
	global_load_lds_dwordx4 v[210:211], off
	s_add_i32 m0, s42, 0x2000
	s_add_u32 s42, s16, 0xb0000
	v_lshl_add_u64 v[212:213], s[16:17], 0, v[168:169]
	s_addc_u32 s43, s17, 0
	s_add_i32 s44, s44, s20
	global_load_lds_dwordx4 v[212:213], off
	v_lshl_add_u64 v[214:215], s[42:43], 0, v[170:171]
	s_mov_b32 m0, s44
	v_lshl_add_u64 v[216:217], s[18:19], 0, v[168:169]
	global_load_lds_dwordx4 v[214:215], off
	v_lshl_add_u64 v[214:215], s[42:43], 0, v[168:169]
	s_add_i32 m0, s44, 0x2000
	s_nop 0
	global_load_lds_dwordx4 v[214:215], off
	s_waitcnt vmcnt(6)
	s_waitcnt lgkmcnt(0)
	s_barrier
; #define PG8_STAGE(bufoff, gbase, voff) do { _Pragma("unroll") for (int _i = 0; _i < 2; ++_i) \
;         __builtin_amdgcn_global_load_lds((const unsigned*)((const char*)(gbase) + (voff)[_i]), (LAS unsigned*)(lds + (bufoff) + ldsw + _i * 8192), 16, 0, 0); } while (0)
; #define PG8_LDA(dst, b, h) do { _Pragma("unroll") for (int m = 0; m < 4; ++m) _Pragma("unroll") for (int k = 0; k < 2; ++k) dst[m][k] = *(const LAS bf16x8*)(lds + PG8_SA(b, h) + aoff + m * 2048 + k * 1024); } while (0)
; #define PG8_LDB(dst, b, h) do { _Pragma("unroll") for (int n = 0; n < 2; ++n) _Pragma("unroll") for (int k = 0; k < 2; ++k) dst[n][k] = *(const LAS bf16x8*)(lds + PG8_SB(b, h) + boff + n * 2048 + k * 1024); } while (0)
; #define PG8_MMA(ai, bj, At, Bt) do { __builtin_amdgcn_s_setprio(1); _Pragma("unroll") for (int m = 0; m < 4; ++m) _Pragma("unroll") for (int n = 0; n < 2; ++n) _Pragma("unroll") for (int k = 0; k < 2; ++k) \
;         acc[ai][bj][m][n] = __builtin_amdgcn_mfma_f32_16x16x32_bf16(Bt[n][k], At[m][k], acc[ai][bj][m][n], 0, 0, 0); __builtin_amdgcn_s_setprio(0); } while (0)
; #define PG8_WAIT_V(n) asm volatile("s_waitcnt vmcnt(" #n ")" ::: "memory")
; #define PG8_WAIT_L(n) asm volatile("s_waitcnt lgkmcnt(" #n ")" ::: "memory")
; #define PG8_BAR __builtin_amdgcn_s_barrier()
; #define PG8_SCHED __builtin_amdgcn_sched_barrier(0)
; template <class Epi, class Sched, bool ALIGN_EPI>
; DI void gemm_phase(LAS unsigned char* lds, const Gemm g, const Sched& S, const Epi& E) {
;     ...
;             PG8_WAIT_V(8); PG8_WAIT_L(0); PG8_BAR; PG8_MMA(1, 0, At, B0); PG8_MMA(1, 1, At, B1); PG8_BAR; PG8_SCHED;
;             PG8_LDB(B0, 1, 0); PG8_LDB(B1, 1, 1); PG8_SCHED; PG8_LDA(At, 1, 0); PG8_STAGE(PG8_SA(0, 1), a2 + hstep, voffA);
;             PG8_WAIT_V(8); PG8_WAIT_L(0); PG8_BAR; PG8_MMA(0, 0, At, B0); PG8_MMA(0, 1, At, B1); PG8_BAR; PG8_SCHED;
	s_setprio 1
	s_waitcnt lgkmcnt(0)
	v_mfma_f32_16x16x32_bf16 v[60:63], v[128:131], v[160:163], v[60:63]
	v_mfma_f32_16x16x32_bf16 v[56:59], v[136:139], v[160:163], v[56:59]
	v_mfma_f32_16x16x32_bf16 v[48:51], v[128:131], v[186:189], v[48:51]
	v_mfma_f32_16x16x32_bf16 v[40:43], v[136:139], v[186:189], v[40:43]
	v_mfma_f32_16x16x32_bf16 v[32:35], v[128:131], v[194:197], v[32:35]
	v_mfma_f32_16x16x32_bf16 v[24:27], v[136:139], v[194:197], v[24:27]
	v_mfma_f32_16x16x32_bf16 v[16:19], v[128:131], v[202:205], v[16:19]
	v_mfma_f32_16x16x32_bf16 v[8:11], v[136:139], v[202:205], v[8:11]
	v_mfma_f32_16x16x32_bf16 v[60:63], v[132:135], v[182:185], v[60:63]
	v_mfma_f32_16x16x32_bf16 v[56:59], v[140:143], v[182:185], v[56:59]
	v_mfma_f32_16x16x32_bf16 v[48:51], v[132:135], v[190:193], v[48:51]
	v_mfma_f32_16x16x32_bf16 v[40:43], v[140:143], v[190:193], v[40:43]
	v_mfma_f32_16x16x32_bf16 v[32:35], v[132:135], v[198:201], v[32:35]
	v_mfma_f32_16x16x32_bf16 v[24:27], v[140:143], v[198:201], v[24:27]
	v_mfma_f32_16x16x32_bf16 v[16:19], v[132:135], v[206:209], v[16:19]
	v_mfma_f32_16x16x32_bf16 v[8:11], v[140:143], v[206:209], v[8:11]
	s_setprio 0
	s_setprio 1
	v_mfma_f32_16x16x32_bf16 v[52:55], v[144:147], v[160:163], v[52:55]
	v_mfma_f32_16x16x32_bf16 v[44:47], v[152:155], v[160:163], v[44:47]
	v_mfma_f32_16x16x32_bf16 v[36:39], v[144:147], v[186:189], v[36:39]
	v_mfma_f32_16x16x32_bf16 v[28:31], v[152:155], v[186:189], v[28:31]
	v_mfma_f32_16x16x32_bf16 v[20:23], v[144:147], v[194:197], v[20:23]
	v_mfma_f32_16x16x32_bf16 v[12:15], v[152:155], v[194:197], v[12:15]
	v_mfma_f32_16x16x32_bf16 v[4:7], v[144:147], v[202:205], v[4:7]
	v_mfma_f32_16x16x32_bf16 v[0:3], v[152:155], v[202:205], v[0:3]
	v_mfma_f32_16x16x32_bf16 v[52:55], v[148:151], v[182:185], v[52:55]
	v_mfma_f32_16x16x32_bf16 v[44:47], v[156:159], v[182:185], v[44:47]
	v_mfma_f32_16x16x32_bf16 v[36:39], v[148:151], v[190:193], v[36:39]
	v_mfma_f32_16x16x32_bf16 v[28:31], v[156:159], v[190:193], v[28:31]
	v_mfma_f32_16x16x32_bf16 v[20:23], v[148:151], v[198:201], v[20:23]
	v_mfma_f32_16x16x32_bf16 v[12:15], v[156:159], v[198:201], v[12:15]
	v_mfma_f32_16x16x32_bf16 v[4:7], v[148:151], v[206:209], v[4:7]
	v_mfma_f32_16x16x32_bf16 v[0:3], v[156:159], v[206:209], v[0:3]
	s_setprio 0
	s_barrier
	s_add_i32 s42, 0, 0x18000
	s_add_i32 s43, 0, 0x1c000
	v_add_u32_e32 v140, s42, v165
	v_add_u32_e32 v156, s43, v165
	ds_read_b128 v[128:131], v140
	ds_read_b128 v[132:135], v140 offset:1024
	ds_read_b128 v[136:139], v140 offset:2048
	ds_read_b128 v[140:143], v140 offset:3072
	ds_read_b128 v[144:147], v156
	ds_read_b128 v[148:151], v156 offset:1024
	ds_read_b128 v[152:155], v156 offset:2048
	ds_read_b128 v[156:159], v156 offset:3072
	v_lshl_add_u64 v[214:215], s[18:19], 0, v[170:171]
	s_mov_b32 m0, s23
	s_nop 0
	global_load_lds_dwordx4 v[214:215], off
	s_mov_b32 m0, s24
	s_nop 0
	global_load_lds_dwordx4 v[216:217], off
	s_add_u32 s18, s18, 0xb0000
	s_addc_u32 s19, s19, 0
	s_mov_b32 m0, s25
	v_lshl_add_u64 v[218:219], s[18:19], 0, v[170:171]
	ds_read_b128 v[160:163], v167 offset:32768
	ds_read_b128 v[182:185], v167 offset:33792
	ds_read_b128 v[186:189], v167 offset:34816
	ds_read_b128 v[190:193], v167 offset:35840
	ds_read_b128 v[194:197], v167 offset:36864
	ds_read_b128 v[198:201], v167 offset:37888
	ds_read_b128 v[202:205], v167 offset:38912
	ds_read_b128 v[206:209], v167 offset:39936
	global_load_lds_dwordx4 v[218:219], off
	v_lshl_add_u64 v[218:219], s[18:19], 0, v[168:169]
	s_mov_b32 m0, s26
	s_nop 0
	global_load_lds_dwordx4 v[218:219], off
	s_waitcnt vmcnt(8)
	s_waitcnt lgkmcnt(0)
	s_barrier
	s_setprio 1
	s_waitcnt lgkmcnt(0)
	v_mfma_f32_16x16x32_bf16 v[124:127], v[128:131], v[160:163], v[124:127]
	v_mfma_f32_16x16x32_bf16 v[120:123], v[136:139], v[160:163], v[120:123]
	v_mfma_f32_16x16x32_bf16 v[108:111], v[128:131], v[186:189], v[108:111]
	v_mfma_f32_16x16x32_bf16 v[104:107], v[136:139], v[186:189], v[104:107]
	v_mfma_f32_16x16x32_bf16 v[96:99], v[128:131], v[194:197], v[96:99]
	v_mfma_f32_16x16x32_bf16 v[88:91], v[136:139], v[194:197], v[88:91]
	v_mfma_f32_16x16x32_bf16 v[80:83], v[128:131], v[202:205], v[80:83]
	v_mfma_f32_16x16x32_bf16 v[72:75], v[136:139], v[202:205], v[72:75]
	v_mfma_f32_16x16x32_bf16 v[124:127], v[132:135], v[182:185], v[124:127]
	v_mfma_f32_16x16x32_bf16 v[120:123], v[140:143], v[182:185], v[120:123]
	v_mfma_f32_16x16x32_bf16 v[108:111], v[132:135], v[190:193], v[108:111]
	v_mfma_f32_16x16x32_bf16 v[104:107], v[140:143], v[190:193], v[104:107]
	v_mfma_f32_16x16x32_bf16 v[96:99], v[132:135], v[198:201], v[96:99]
	v_mfma_f32_16x16x32_bf16 v[88:91], v[140:143], v[198:201], v[88:91]
	v_mfma_f32_16x16x32_bf16 v[80:83], v[132:135], v[206:209], v[80:83]
	v_mfma_f32_16x16x32_bf16 v[72:75], v[140:143], v[206:209], v[72:75]
	s_setprio 0
	s_setprio 1
	v_mfma_f32_16x16x32_bf16 v[116:119], v[144:147], v[160:163], v[116:119]
	v_mfma_f32_16x16x32_bf16 v[112:115], v[152:155], v[160:163], v[112:115]
	v_mfma_f32_16x16x32_bf16 v[100:103], v[144:147], v[186:189], v[100:103]
	v_mfma_f32_16x16x32_bf16 v[92:95], v[152:155], v[186:189], v[92:95]
	v_mfma_f32_16x16x32_bf16 v[84:87], v[144:147], v[194:197], v[84:87]
	v_mfma_f32_16x16x32_bf16 v[76:79], v[152:155], v[194:197], v[76:79]
	v_mfma_f32_16x16x32_bf16 v[68:71], v[144:147], v[202:205], v[68:71]
	v_mfma_f32_16x16x32_bf16 v[64:67], v[152:155], v[202:205], v[64:67]
	v_mfma_f32_16x16x32_bf16 v[116:119], v[148:151], v[182:185], v[116:119]
	v_mfma_f32_16x16x32_bf16 v[112:115], v[156:159], v[182:185], v[112:115]
	v_mfma_f32_16x16x32_bf16 v[100:103], v[148:151], v[190:193], v[100:103]
	v_mfma_f32_16x16x32_bf16 v[92:95], v[156:159], v[190:193], v[92:95]
	v_mfma_f32_16x16x32_bf16 v[84:87], v[148:151], v[198:201], v[84:87]
	v_mfma_f32_16x16x32_bf16 v[76:79], v[156:159], v[198:201], v[76:79]
	v_mfma_f32_16x16x32_bf16 v[68:71], v[148:151], v[206:209], v[68:71]
	v_mfma_f32_16x16x32_bf16 v[64:67], v[156:159], v[206:209], v[64:67]
	s_setprio 0
	s_barrier
; #define PG8_STAGE(bufoff, gbase, voff) do { _Pragma("unroll") for (int _i = 0; _i < 2; ++_i) \
;         __builtin_amdgcn_global_load_lds((const unsigned*)((const char*)(gbase) + (voff)[_i]), (LAS unsigned*)(lds + (bufoff) + ldsw + _i * 8192), 16, 0, 0); } while (0)
; #define PG8_LDA(dst, b, h) do { _Pragma("unroll") for (int m = 0; m < 4; ++m) _Pragma("unroll") for (int k = 0; k < 2; ++k) dst[m][k] = *(const LAS bf16x8*)(lds + PG8_SA(b, h) + aoff + m * 2048 + k * 1024); } while (0)
; #define PG8_MMA(ai, bj, At, Bt) do { __builtin_amdgcn_s_setprio(1); _Pragma("unroll") for (int m = 0; m < 4; ++m) _Pragma("unroll") for (int n = 0; n < 2; ++n) _Pragma("unroll") for (int k = 0; k < 2; ++k) \
;         acc[ai][bj][m][n] = __builtin_amdgcn_mfma_f32_16x16x32_bf16(Bt[n][k], At[m][k], acc[ai][bj][m][n], 0, 0, 0); __builtin_amdgcn_s_setprio(0); } while (0)
; #define PG8_WAIT_V(n) asm volatile("s_waitcnt vmcnt(" #n ")" ::: "memory")
; #define PG8_WAIT_L(n) asm volatile("s_waitcnt lgkmcnt(" #n ")" ::: "memory")
; #define PG8_BAR __builtin_amdgcn_s_barrier()
; #define PG8_SCHED __builtin_amdgcn_sched_barrier(0)
; template <class Epi, class Sched, bool ALIGN_EPI>
; DI void gemm_phase(LAS unsigned char* lds, const Gemm g, const Sched& S, const Epi& E) {
;     ...
;             PG8_LDA(At, 1, 1); PG8_STAGE(PG8_SB(1, 0), b3, voffA); PG8_STAGE(PG8_SB(1, 1), b3 + hstep, voffA); PG8_STAGE(PG8_SA(1, 0), a3, voffA);
;             PG8_WAIT_V(8); PG8_WAIT_L(0); PG8_BAR; PG8_MMA(1, 0, At, B0); PG8_MMA(1, 1, At, B1); PG8_BAR; PG8_SCHED;
;         }
	s_add_i32 s18, s42, s20
	v_lshl_add_u64 v[210:211], v[210:211], 0, s[2:3]
	s_mov_b32 m0, s18
	ds_read_b128 v[160:163], v167 offset:49152
	ds_read_b128 v[182:185], v167 offset:50176
	ds_read_b128 v[186:189], v167 offset:51200
	ds_read_b128 v[190:193], v167 offset:52224
	ds_read_b128 v[194:197], v167 offset:53248
	ds_read_b128 v[198:201], v167 offset:54272
	ds_read_b128 v[202:205], v167 offset:55296
	ds_read_b128 v[206:209], v167 offset:56320
	global_load_lds_dwordx4 v[210:211], off
	s_add_i32 m0, s18, 0x2000
	s_add_u32 s16, s16, 0xb0080
	v_lshl_add_u64 v[210:211], v[212:213], 0, s[2:3]
	s_addc_u32 s17, s17, 0
	s_add_i32 s18, s43, s20
	global_load_lds_dwordx4 v[210:211], off
	v_lshl_add_u64 v[210:211], s[16:17], 0, v[170:171]
	s_mov_b32 m0, s18
	s_nop 0
	global_load_lds_dwordx4 v[210:211], off
	v_lshl_add_u64 v[210:211], s[16:17], 0, v[168:169]
	s_add_i32 m0, s18, 0x2000
	s_nop 0
	global_load_lds_dwordx4 v[210:211], off
	v_lshl_add_u64 v[210:211], v[214:215], 0, s[2:3]
	s_mov_b32 m0, s27
	s_nop 0
	global_load_lds_dwordx4 v[210:211], off
	v_lshl_add_u64 v[210:211], v[216:217], 0, s[2:3]
	s_mov_b32 m0, s28
	s_nop 0
	global_load_lds_dwordx4 v[210:211], off
	s_waitcnt vmcnt(8)
	s_waitcnt lgkmcnt(0)
	s_barrier
	s_setprio 1
	s_waitcnt lgkmcnt(0)
	v_mfma_f32_16x16x32_bf16 v[60:63], v[128:131], v[160:163], v[60:63]
	v_mfma_f32_16x16x32_bf16 v[56:59], v[136:139], v[160:163], v[56:59]
	v_mfma_f32_16x16x32_bf16 v[48:51], v[128:131], v[186:189], v[48:51]
	v_mfma_f32_16x16x32_bf16 v[40:43], v[136:139], v[186:189], v[40:43]
	v_mfma_f32_16x16x32_bf16 v[32:35], v[128:131], v[194:197], v[32:35]
	v_mfma_f32_16x16x32_bf16 v[24:27], v[136:139], v[194:197], v[24:27]
	v_mfma_f32_16x16x32_bf16 v[16:19], v[128:131], v[202:205], v[16:19]
	v_mfma_f32_16x16x32_bf16 v[8:11], v[136:139], v[202:205], v[8:11]
	v_mfma_f32_16x16x32_bf16 v[60:63], v[132:135], v[182:185], v[60:63]
	v_mfma_f32_16x16x32_bf16 v[56:59], v[140:143], v[182:185], v[56:59]
	v_mfma_f32_16x16x32_bf16 v[48:51], v[132:135], v[190:193], v[48:51]
	v_mfma_f32_16x16x32_bf16 v[40:43], v[140:143], v[190:193], v[40:43]
	v_mfma_f32_16x16x32_bf16 v[32:35], v[132:135], v[198:201], v[32:35]
	v_mfma_f32_16x16x32_bf16 v[24:27], v[140:143], v[198:201], v[24:27]
	v_mfma_f32_16x16x32_bf16 v[16:19], v[132:135], v[206:209], v[16:19]
	v_mfma_f32_16x16x32_bf16 v[8:11], v[140:143], v[206:209], v[8:11]
	s_setprio 0
	s_setprio 1
	v_mfma_f32_16x16x32_bf16 v[52:55], v[144:147], v[160:163], v[52:55]
	v_mfma_f32_16x16x32_bf16 v[44:47], v[152:155], v[160:163], v[44:47]
	v_mfma_f32_16x16x32_bf16 v[36:39], v[144:147], v[186:189], v[36:39]
	v_mfma_f32_16x16x32_bf16 v[28:31], v[152:155], v[186:189], v[28:31]
	v_mfma_f32_16x16x32_bf16 v[20:23], v[144:147], v[194:197], v[20:23]
	v_mfma_f32_16x16x32_bf16 v[12:15], v[152:155], v[194:197], v[12:15]
	v_mfma_f32_16x16x32_bf16 v[4:7], v[144:147], v[202:205], v[4:7]
	v_mfma_f32_16x16x32_bf16 v[0:3], v[152:155], v[202:205], v[0:3]
	v_mfma_f32_16x16x32_bf16 v[52:55], v[148:151], v[182:185], v[52:55]
	v_mfma_f32_16x16x32_bf16 v[44:47], v[156:159], v[182:185], v[44:47]
	v_mfma_f32_16x16x32_bf16 v[36:39], v[148:151], v[190:193], v[36:39]
	v_mfma_f32_16x16x32_bf16 v[28:31], v[156:159], v[190:193], v[28:31]
	v_mfma_f32_16x16x32_bf16 v[20:23], v[148:151], v[198:201], v[20:23]
	v_mfma_f32_16x16x32_bf16 v[12:15], v[156:159], v[198:201], v[12:15]
	v_mfma_f32_16x16x32_bf16 v[4:7], v[148:151], v[206:209], v[4:7]
	v_mfma_f32_16x16x32_bf16 v[0:3], v[156:159], v[206:209], v[0:3]
	s_setprio 0
	s_barrier
	s_add_i32 s37, s37, 2
	s_add_u32 s0, s0, 0x100
	s_addc_u32 s1, s1, 0
	s_add_u32 s35, s35, 0x100
	s_addc_u32 s36, s36, 0
	s_cmp_gt_u32 s37, 41
	s_cbranch_scc0 .LBB0_791
	s_and_b64 vcc, exec, s[10:11]
	s_cbranch_vccz .LBB0_794
	s_barrier

; #define PG8_STAGE(bufoff, gbase, voff) do { _Pragma("unroll") for (int _i = 0; _i < 2; ++_i) \
;         __builtin_amdgcn_global_load_lds((const unsigned*)((const char*)(gbase) + (voff)[_i]), (LAS unsigned*)(lds + (bufoff) + ldsw + _i * 8192), 16, 0, 0); } while (0)
; #define PG8_LDA(dst, b, h) do { _Pragma("unroll") for (int m = 0; m < 4; ++m) _Pragma("unroll") for (int k = 0; k < 2; ++k) dst[m][k] = *(const LAS bf16x8*)(lds + PG8_SA(b, h) + aoff + m * 2048 + k * 1024); } while (0)
; #define PG8_LDB(dst, b, h) do { _Pragma("unroll") for (int n = 0; n < 2; ++n) _Pragma("unroll") for (int k = 0; k < 2; ++k) dst[n][k] = *(const LAS bf16x8*)(lds + PG8_SB(b, h) + boff + n * 2048 + k * 1024); } while (0)
; #define PG8_MMA(ai, bj, At, Bt) do { __builtin_amdgcn_s_setprio(1); _Pragma("unroll") for (int m = 0; m < 4; ++m) _Pragma("unroll") for (int n = 0; n < 2; ++n) _Pragma("unroll") for (int k = 0; k < 2; ++k) \
;         acc[ai][bj][m][n] = __builtin_amdgcn_mfma_f32_16x16x32_bf16(Bt[n][k], At[m][k], acc[ai][bj][m][n], 0, 0, 0); __builtin_amdgcn_s_setprio(0); } while (0)
; #define PG8_WAIT_V(n) asm volatile("s_waitcnt vmcnt(" #n ")" ::: "memory")
; #define PG8_WAIT_L(n) asm volatile("s_waitcnt lgkmcnt(" #n ")" ::: "memory")
; #define PG8_BAR __builtin_amdgcn_s_barrier()
; #define PG8_SCHED __builtin_amdgcn_sched_barrier(0)
; template <class Epi, class Sched, bool ALIGN_EPI>
; DI void gemm_phase(LAS unsigned char* lds, const Gemm g, const Sched& S, const Epi& E) {
;     ...
;             PG8_LDB(B0, 0, 0); PG8_LDB(B1, 0, 1); PG8_SCHED; PG8_LDA(At, 0, 0); PG8_STAGE(PG8_SA(1, 1), a1 + hstep, voffA);
;             PG8_WAIT_V(8); PG8_WAIT_L(0); PG8_BAR; PG8_MMA(0, 0, At, B0); PG8_MMA(0, 1, At, B1); PG8_BAR; PG8_SCHED;
;             PG8_LDA(At, 0, 1); PG8_STAGE(PG8_SB(0, 0), b2, voffA); PG8_STAGE(PG8_SB(0, 1), b2 + hstep, voffA); PG8_STAGE(PG8_SA(0, 0), a2, voffA);
;             PG8_WAIT_V(8); PG8_WAIT_L(0); PG8_BAR; PG8_MMA(1, 0, At, B0); PG8_MMA(1, 1, At, B1); PG8_BAR; PG8_SCHED;
.LBB0_826:
	s_add_u32 s30, s0, 0xfffc0080
	s_addc_u32 s31, s1, -1
	s_add_i32 s46, 0, 0x10000
	s_cmp_eq_u32 s45, 12
	s_cselect_b32 s35, s25, s31
	s_cselect_b32 s34, s24, s30
	s_cselect_b32 s31, s23, s44
	s_cselect_b32 s30, s29, s43
	s_add_i32 s52, 0, 0x14000
	v_add_u32_e32 v56, s46, v241
	v_add_u32_e32 v136, s52, v241
	ds_read_b128 v[44:47], v56
	ds_read_b128 v[48:51], v56 offset:1024
	ds_read_b128 v[52:55], v56 offset:2048
	ds_read_b128 v[56:59], v56 offset:3072
	ds_read_b128 v[124:127], v136
	ds_read_b128 v[128:131], v136 offset:1024
	ds_read_b128 v[132:135], v136 offset:2048
	ds_read_b128 v[136:139], v136 offset:3072
	v_lshl_add_u64 v[206:207], s[0:1], 0, v[178:179]
	s_add_i32 m0, s93, 0xc000
	ds_read_b128 v[160:163], v245
	ds_read_b128 v[164:167], v245 offset:1024
	ds_read_b128 v[182:185], v245 offset:2048
	ds_read_b128 v[186:189], v245 offset:3072
	ds_read_b128 v[190:193], v245 offset:4096
	ds_read_b128 v[194:197], v245 offset:5120
	ds_read_b128 v[198:201], v245 offset:6144
	ds_read_b128 v[202:205], v245 offset:7168
	global_load_lds_dwordx4 v[206:207], off
	v_lshl_add_u64 v[206:207], s[0:1], 0, v[180:181]
	s_add_i32 m0, s93, 0xe000
	s_nop 0
	global_load_lds_dwordx4 v[206:207], off
	s_waitcnt vmcnt(8)
	s_waitcnt lgkmcnt(0)
	s_barrier
	s_setprio 1
	s_waitcnt lgkmcnt(0)
	v_mfma_f32_16x16x32_bf16 v[156:159], v[44:47], v[160:163], v[156:159]
	v_mfma_f32_16x16x32_bf16 v[76:79], v[52:55], v[160:163], v[76:79]
	v_mfma_f32_16x16x32_bf16 v[148:151], v[44:47], v[182:185], v[148:151]
	v_mfma_f32_16x16x32_bf16 v[68:71], v[52:55], v[182:185], v[68:71]
	v_mfma_f32_16x16x32_bf16 v[140:143], v[44:47], v[190:193], v[140:143]
	v_mfma_f32_16x16x32_bf16 v[60:63], v[52:55], v[190:193], v[60:63]
	v_mfma_f32_16x16x32_bf16 v[116:119], v[44:47], v[198:201], v[116:119]
	v_mfma_f32_16x16x32_bf16 v[36:39], v[52:55], v[198:201], v[36:39]
	v_mfma_f32_16x16x32_bf16 v[156:159], v[48:51], v[164:167], v[156:159]
	v_mfma_f32_16x16x32_bf16 v[76:79], v[56:59], v[164:167], v[76:79]
	v_mfma_f32_16x16x32_bf16 v[148:151], v[48:51], v[186:189], v[148:151]
	v_mfma_f32_16x16x32_bf16 v[68:71], v[56:59], v[186:189], v[68:71]
	v_mfma_f32_16x16x32_bf16 v[140:143], v[48:51], v[194:197], v[140:143]
	v_mfma_f32_16x16x32_bf16 v[60:63], v[56:59], v[194:197], v[60:63]
	v_mfma_f32_16x16x32_bf16 v[116:119], v[48:51], v[202:205], v[116:119]
	v_mfma_f32_16x16x32_bf16 v[36:39], v[56:59], v[202:205], v[36:39]
	s_setprio 0
	s_setprio 1
	v_mfma_f32_16x16x32_bf16 v[152:155], v[124:127], v[160:163], v[152:155]
	v_mfma_f32_16x16x32_bf16 v[72:75], v[132:135], v[160:163], v[72:75]
	v_mfma_f32_16x16x32_bf16 v[144:147], v[124:127], v[182:185], v[144:147]
	v_mfma_f32_16x16x32_bf16 v[64:67], v[132:135], v[182:185], v[64:67]
	v_mfma_f32_16x16x32_bf16 v[120:123], v[124:127], v[190:193], v[120:123]
	v_mfma_f32_16x16x32_bf16 v[40:43], v[132:135], v[190:193], v[40:43]
	v_mfma_f32_16x16x32_bf16 v[112:115], v[124:127], v[198:201], v[112:115]
	v_mfma_f32_16x16x32_bf16 v[32:35], v[132:135], v[198:201], v[32:35]
	v_mfma_f32_16x16x32_bf16 v[152:155], v[128:131], v[164:167], v[152:155]
	v_mfma_f32_16x16x32_bf16 v[72:75], v[136:139], v[164:167], v[72:75]
	v_mfma_f32_16x16x32_bf16 v[144:147], v[128:131], v[186:189], v[144:147]
	v_mfma_f32_16x16x32_bf16 v[64:67], v[136:139], v[186:189], v[64:67]
	v_mfma_f32_16x16x32_bf16 v[120:123], v[128:131], v[194:197], v[120:123]
	v_mfma_f32_16x16x32_bf16 v[40:43], v[136:139], v[194:197], v[40:43]
	v_mfma_f32_16x16x32_bf16 v[112:115], v[128:131], v[202:205], v[112:115]
	v_mfma_f32_16x16x32_bf16 v[32:35], v[136:139], v[202:205], v[32:35]
	s_setprio 0
	s_barrier
	s_add_i32 s46, s46, s92
	v_lshl_add_u64 v[206:207], s[30:31], 0, v[174:175]
	s_mov_b32 m0, s46
	ds_read_b128 v[160:163], v245 offset:16384
	ds_read_b128 v[164:167], v245 offset:17408
	ds_read_b128 v[182:185], v245 offset:18432
	ds_read_b128 v[186:189], v245 offset:19456
	ds_read_b128 v[190:193], v245 offset:20480
	ds_read_b128 v[194:197], v245 offset:21504
	ds_read_b128 v[198:201], v245 offset:22528
	ds_read_b128 v[202:205], v245 offset:23552
	global_load_lds_dwordx4 v[206:207], off
	s_add_i32 m0, s46, 0x2000
	s_add_u32 s46, s30, 0x40000
	v_lshl_add_u64 v[208:209], s[30:31], 0, v[176:177]
	s_addc_u32 s47, s31, 0
	s_add_i32 s52, s52, s92
	global_load_lds_dwordx4 v[208:209], off
	v_lshl_add_u64 v[210:211], s[46:47], 0, v[174:175]
	s_mov_b32 m0, s52
	v_lshl_add_u64 v[212:213], s[34:35], 0, v[176:177]
	global_load_lds_dwordx4 v[210:211], off
	v_lshl_add_u64 v[210:211], s[46:47], 0, v[176:177]
	s_add_i32 m0, s52, 0x2000
	s_nop 0
	global_load_lds_dwordx4 v[210:211], off
	s_waitcnt vmcnt(6)
	s_waitcnt lgkmcnt(0)
	s_barrier
; #define PG8_STAGE(bufoff, gbase, voff) do { _Pragma("unroll") for (int _i = 0; _i < 2; ++_i) \
;         __builtin_amdgcn_global_load_lds((const unsigned*)((const char*)(gbase) + (voff)[_i]), (LAS unsigned*)(lds + (bufoff) + ldsw + _i * 8192), 16, 0, 0); } while (0)
; #define PG8_LDA(dst, b, h) do { _Pragma("unroll") for (int m = 0; m < 4; ++m) _Pragma("unroll") for (int k = 0; k < 2; ++k) dst[m][k] = *(const LAS bf16x8*)(lds + PG8_SA(b, h) + aoff + m * 2048 + k * 1024); } while (0)
; #define PG8_LDB(dst, b, h) do { _Pragma("unroll") for (int n = 0; n < 2; ++n) _Pragma("unroll") for (int k = 0; k < 2; ++k) dst[n][k] = *(const LAS bf16x8*)(lds + PG8_SB(b, h) + boff + n * 2048 + k * 1024); } while (0)
; #define PG8_MMA(ai, bj, At, Bt) do { __builtin_amdgcn_s_setprio(1); _Pragma("unroll") for (int m = 0; m < 4; ++m) _Pragma("unroll") for (int n = 0; n < 2; ++n) _Pragma("unroll") for (int k = 0; k < 2; ++k) \
;         acc[ai][bj][m][n] = __builtin_amdgcn_mfma_f32_16x16x32_bf16(Bt[n][k], At[m][k], acc[ai][bj][m][n], 0, 0, 0); __builtin_amdgcn_s_setprio(0); } while (0)
; #define PG8_WAIT_V(n) asm volatile("s_waitcnt vmcnt(" #n ")" ::: "memory")
; #define PG8_WAIT_L(n) asm volatile("s_waitcnt lgkmcnt(" #n ")" ::: "memory")
; #define PG8_BAR __builtin_amdgcn_s_barrier()
; #define PG8_SCHED __builtin_amdgcn_sched_barrier(0)
; template <class Epi, class Sched, bool ALIGN_EPI>
; DI void gemm_phase(LAS unsigned char* lds, const Gemm g, const Sched& S, const Epi& E) {
;     ...
;             PG8_WAIT_V(8); PG8_WAIT_L(0); PG8_BAR; PG8_MMA(1, 0, At, B0); PG8_MMA(1, 1, At, B1); PG8_BAR; PG8_SCHED;
;             PG8_LDB(B0, 1, 0); PG8_LDB(B1, 1, 1); PG8_SCHED; PG8_LDA(At, 1, 0); PG8_STAGE(PG8_SA(0, 1), a2 + hstep, voffA);
;             PG8_WAIT_V(8); PG8_WAIT_L(0); PG8_BAR; PG8_MMA(0, 0, At, B0); PG8_MMA(0, 1, At, B1); PG8_BAR; PG8_SCHED;
	s_setprio 1
	s_waitcnt lgkmcnt(0)
	v_mfma_f32_16x16x32_bf16 v[108:111], v[44:47], v[160:163], v[108:111]
	v_mfma_f32_16x16x32_bf16 v[28:31], v[52:55], v[160:163], v[28:31]
	v_mfma_f32_16x16x32_bf16 v[100:103], v[44:47], v[182:185], v[100:103]
	v_mfma_f32_16x16x32_bf16 v[20:23], v[52:55], v[182:185], v[20:23]
	v_mfma_f32_16x16x32_bf16 v[92:95], v[44:47], v[190:193], v[92:95]
	v_mfma_f32_16x16x32_bf16 v[12:15], v[52:55], v[190:193], v[12:15]
	v_mfma_f32_16x16x32_bf16 v[4:7], v[52:55], v[198:201], v[4:7]
	v_mfma_f32_16x16x32_bf16 v[108:111], v[48:51], v[164:167], v[108:111]
	v_mfma_f32_16x16x32_bf16 v[28:31], v[56:59], v[164:167], v[28:31]
	v_mfma_f32_16x16x32_bf16 v[100:103], v[48:51], v[186:189], v[100:103]
	v_mfma_f32_16x16x32_bf16 v[20:23], v[56:59], v[186:189], v[20:23]
	v_mfma_f32_16x16x32_bf16 v[92:95], v[48:51], v[194:197], v[92:95]
	v_mfma_f32_16x16x32_bf16 v[12:15], v[56:59], v[194:197], v[12:15]
	v_mfma_f32_16x16x32_bf16 v[44:47], v[44:47], v[198:201], v[84:87]
	v_mfma_f32_16x16x32_bf16 v[4:7], v[56:59], v[202:205], v[4:7]
	v_mfma_f32_16x16x32_bf16 v[44:47], v[48:51], v[202:205], v[44:47]
	s_setprio 0
	s_setprio 1
	v_mfma_f32_16x16x32_bf16 v[24:27], v[132:135], v[160:163], v[24:27]
	v_mfma_f32_16x16x32_bf16 v[16:19], v[132:135], v[182:185], v[16:19]
	v_mfma_f32_16x16x32_bf16 v[8:11], v[132:135], v[190:193], v[8:11]
	v_mfma_f32_16x16x32_bf16 v[80:83], v[124:127], v[198:201], v[80:83]
	v_mfma_f32_16x16x32_bf16 v[0:3], v[132:135], v[198:201], v[0:3]
	v_mfma_f32_16x16x32_bf16 v[48:51], v[124:127], v[160:163], v[104:107]
	v_mfma_f32_16x16x32_bf16 v[24:27], v[136:139], v[164:167], v[24:27]
	v_mfma_f32_16x16x32_bf16 v[52:55], v[124:127], v[182:185], v[96:99]
	v_mfma_f32_16x16x32_bf16 v[16:19], v[136:139], v[186:189], v[16:19]
	v_mfma_f32_16x16x32_bf16 v[56:59], v[124:127], v[190:193], v[88:91]
	v_mfma_f32_16x16x32_bf16 v[8:11], v[136:139], v[194:197], v[8:11]
	v_mfma_f32_16x16x32_bf16 v[80:83], v[128:131], v[202:205], v[80:83]
	v_mfma_f32_16x16x32_bf16 v[0:3], v[136:139], v[202:205], v[0:3]
	v_mfma_f32_16x16x32_bf16 v[48:51], v[128:131], v[164:167], v[48:51]
	v_mfma_f32_16x16x32_bf16 v[52:55], v[128:131], v[186:189], v[52:55]
	v_mfma_f32_16x16x32_bf16 v[56:59], v[128:131], v[194:197], v[56:59]
	s_setprio 0
	s_barrier
	s_add_i32 s46, 0, 0x18000
	s_add_i32 s47, 0, 0x1c000
	v_add_u32_e32 v104, s46, v241
	v_add_u32_e32 v136, s47, v241
	ds_read_b128 v[84:87], v104
	ds_read_b128 v[88:91], v104 offset:1024
	ds_read_b128 v[96:99], v104 offset:2048
	ds_read_b128 v[104:107], v104 offset:3072
	ds_read_b128 v[124:127], v136
	ds_read_b128 v[128:131], v136 offset:1024
	ds_read_b128 v[132:135], v136 offset:2048
	ds_read_b128 v[136:139], v136 offset:3072
	v_lshl_add_u64 v[210:211], s[34:35], 0, v[174:175]
	s_mov_b32 m0, s93
	s_nop 0
	global_load_lds_dwordx4 v[210:211], off
	s_mov_b32 m0, s86
	s_nop 0
	global_load_lds_dwordx4 v[212:213], off
	s_add_u32 s34, s34, 0x40000
	s_addc_u32 s35, s35, 0
	s_mov_b32 m0, s33
	v_lshl_add_u64 v[214:215], s[34:35], 0, v[174:175]
	ds_read_b128 v[160:163], v245 offset:32768
	ds_read_b128 v[164:167], v245 offset:33792
	ds_read_b128 v[182:185], v245 offset:34816
	ds_read_b128 v[186:189], v245 offset:35840
	ds_read_b128 v[190:193], v245 offset:36864
	ds_read_b128 v[194:197], v245 offset:37888
	ds_read_b128 v[198:201], v245 offset:38912
	ds_read_b128 v[202:205], v245 offset:39936
	global_load_lds_dwordx4 v[214:215], off
	v_lshl_add_u64 v[214:215], s[34:35], 0, v[176:177]
	s_mov_b32 m0, s78
	s_nop 0
	global_load_lds_dwordx4 v[214:215], off
	s_waitcnt vmcnt(8)
	s_waitcnt lgkmcnt(0)
	s_barrier
	s_setprio 1
	s_waitcnt lgkmcnt(0)
	v_mfma_f32_16x16x32_bf16 v[156:159], v[84:87], v[160:163], v[156:159]
	v_mfma_f32_16x16x32_bf16 v[76:79], v[96:99], v[160:163], v[76:79]
	v_mfma_f32_16x16x32_bf16 v[148:151], v[84:87], v[182:185], v[148:151]
	v_mfma_f32_16x16x32_bf16 v[68:71], v[96:99], v[182:185], v[68:71]
	v_mfma_f32_16x16x32_bf16 v[140:143], v[84:87], v[190:193], v[140:143]
	v_mfma_f32_16x16x32_bf16 v[60:63], v[96:99], v[190:193], v[60:63]
	v_mfma_f32_16x16x32_bf16 v[116:119], v[84:87], v[198:201], v[116:119]
	v_mfma_f32_16x16x32_bf16 v[36:39], v[96:99], v[198:201], v[36:39]
	v_mfma_f32_16x16x32_bf16 v[156:159], v[88:91], v[164:167], v[156:159]
	v_mfma_f32_16x16x32_bf16 v[76:79], v[104:107], v[164:167], v[76:79]
	v_mfma_f32_16x16x32_bf16 v[148:151], v[88:91], v[186:189], v[148:151]
	v_mfma_f32_16x16x32_bf16 v[68:71], v[104:107], v[186:189], v[68:71]
	v_mfma_f32_16x16x32_bf16 v[140:143], v[88:91], v[194:197], v[140:143]
	v_mfma_f32_16x16x32_bf16 v[60:63], v[104:107], v[194:197], v[60:63]
	v_mfma_f32_16x16x32_bf16 v[116:119], v[88:91], v[202:205], v[116:119]
	v_mfma_f32_16x16x32_bf16 v[36:39], v[104:107], v[202:205], v[36:39]
	s_setprio 0
	s_setprio 1
	v_mfma_f32_16x16x32_bf16 v[152:155], v[124:127], v[160:163], v[152:155]
	v_mfma_f32_16x16x32_bf16 v[72:75], v[132:135], v[160:163], v[72:75]
	v_mfma_f32_16x16x32_bf16 v[144:147], v[124:127], v[182:185], v[144:147]
	v_mfma_f32_16x16x32_bf16 v[64:67], v[132:135], v[182:185], v[64:67]
	v_mfma_f32_16x16x32_bf16 v[120:123], v[124:127], v[190:193], v[120:123]
	v_mfma_f32_16x16x32_bf16 v[40:43], v[132:135], v[190:193], v[40:43]
	v_mfma_f32_16x16x32_bf16 v[112:115], v[124:127], v[198:201], v[112:115]
	v_mfma_f32_16x16x32_bf16 v[32:35], v[132:135], v[198:201], v[32:35]
	v_mfma_f32_16x16x32_bf16 v[152:155], v[128:131], v[164:167], v[152:155]
	v_mfma_f32_16x16x32_bf16 v[72:75], v[136:139], v[164:167], v[72:75]
	v_mfma_f32_16x16x32_bf16 v[144:147], v[128:131], v[186:189], v[144:147]
	v_mfma_f32_16x16x32_bf16 v[64:67], v[136:139], v[186:189], v[64:67]
	v_mfma_f32_16x16x32_bf16 v[120:123], v[128:131], v[194:197], v[120:123]
	v_mfma_f32_16x16x32_bf16 v[40:43], v[136:139], v[194:197], v[40:43]
	v_mfma_f32_16x16x32_bf16 v[112:115], v[128:131], v[202:205], v[112:115]
	v_mfma_f32_16x16x32_bf16 v[32:35], v[136:139], v[202:205], v[32:35]
	s_setprio 0
	s_barrier
; #define PG8_STAGE(bufoff, gbase, voff) do { _Pragma("unroll") for (int _i = 0; _i < 2; ++_i) \
;         __builtin_amdgcn_global_load_lds((const unsigned*)((const char*)(gbase) + (voff)[_i]), (LAS unsigned*)(lds + (bufoff) + ldsw + _i * 8192), 16, 0, 0); } while (0)
; #define PG8_LDA(dst, b, h) do { _Pragma("unroll") for (int m = 0; m < 4; ++m) _Pragma("unroll") for (int k = 0; k < 2; ++k) dst[m][k] = *(const LAS bf16x8*)(lds + PG8_SA(b, h) + aoff + m * 2048 + k * 1024); } while (0)
; #define PG8_MMA(ai, bj, At, Bt) do { __builtin_amdgcn_s_setprio(1); _Pragma("unroll") for (int m = 0; m < 4; ++m) _Pragma("unroll") for (int n = 0; n < 2; ++n) _Pragma("unroll") for (int k = 0; k < 2; ++k) \
;         acc[ai][bj][m][n] = __builtin_amdgcn_mfma_f32_16x16x32_bf16(Bt[n][k], At[m][k], acc[ai][bj][m][n], 0, 0, 0); __builtin_amdgcn_s_setprio(0); } while (0)
; #define PG8_WAIT_V(n) asm volatile("s_waitcnt vmcnt(" #n ")" ::: "memory")
; #define PG8_WAIT_L(n) asm volatile("s_waitcnt lgkmcnt(" #n ")" ::: "memory")
; #define PG8_BAR __builtin_amdgcn_s_barrier()
; #define PG8_SCHED __builtin_amdgcn_sched_barrier(0)
; template <class Epi, class Sched, bool ALIGN_EPI>
; DI void gemm_phase(LAS unsigned char* lds, const Gemm g, const Sched& S, const Epi& E) {
;     ...
;             PG8_LDA(At, 1, 1); PG8_STAGE(PG8_SB(1, 0), b3, voffA); PG8_STAGE(PG8_SB(1, 1), b3 + hstep, voffA); PG8_STAGE(PG8_SA(1, 0), a3, voffA);
;             PG8_WAIT_V(8); PG8_WAIT_L(0); PG8_BAR; PG8_MMA(1, 0, At, B0); PG8_MMA(1, 1, At, B1); PG8_BAR; PG8_SCHED;
;         }
	s_add_i32 s34, s46, s92
	v_lshl_add_u64 v[206:207], v[206:207], 0, s[2:3]
	s_mov_b32 m0, s34
	ds_read_b128 v[160:163], v245 offset:49152
	ds_read_b128 v[164:167], v245 offset:50176
	ds_read_b128 v[182:185], v245 offset:51200
	ds_read_b128 v[186:189], v245 offset:52224
	ds_read_b128 v[190:193], v245 offset:53248
	ds_read_b128 v[194:197], v245 offset:54272
	ds_read_b128 v[198:201], v245 offset:55296
	ds_read_b128 v[202:205], v245 offset:56320
	global_load_lds_dwordx4 v[206:207], off
	s_add_i32 m0, s34, 0x2000
	s_add_u32 s30, s30, 0x40080
	v_lshl_add_u64 v[206:207], v[208:209], 0, s[2:3]
	s_addc_u32 s31, s31, 0
	s_add_i32 s34, s47, s92
	global_load_lds_dwordx4 v[206:207], off
	v_lshl_add_u64 v[206:207], s[30:31], 0, v[174:175]
	s_mov_b32 m0, s34
	s_nop 0
	global_load_lds_dwordx4 v[206:207], off
	v_lshl_add_u64 v[206:207], s[30:31], 0, v[176:177]
	s_add_i32 m0, s34, 0x2000
	s_nop 0
	global_load_lds_dwordx4 v[206:207], off
	v_lshl_add_u64 v[206:207], v[210:211], 0, s[2:3]
	s_mov_b32 m0, s8
	s_nop 0
	global_load_lds_dwordx4 v[206:207], off
	v_lshl_add_u64 v[206:207], v[212:213], 0, s[2:3]
	s_mov_b32 m0, s9
	s_nop 0
	global_load_lds_dwordx4 v[206:207], off
	s_waitcnt vmcnt(8)
	s_waitcnt lgkmcnt(0)
	s_barrier
	s_setprio 1
	s_waitcnt lgkmcnt(0)
	v_mfma_f32_16x16x32_bf16 v[108:111], v[84:87], v[160:163], v[108:111]
	v_mfma_f32_16x16x32_bf16 v[28:31], v[96:99], v[160:163], v[28:31]
	v_mfma_f32_16x16x32_bf16 v[100:103], v[84:87], v[182:185], v[100:103]
	v_mfma_f32_16x16x32_bf16 v[20:23], v[96:99], v[182:185], v[20:23]
	v_mfma_f32_16x16x32_bf16 v[92:95], v[84:87], v[190:193], v[92:95]
	v_mfma_f32_16x16x32_bf16 v[12:15], v[96:99], v[190:193], v[12:15]
	v_mfma_f32_16x16x32_bf16 v[44:47], v[84:87], v[198:201], v[44:47]
	v_mfma_f32_16x16x32_bf16 v[4:7], v[96:99], v[198:201], v[4:7]
	v_mfma_f32_16x16x32_bf16 v[108:111], v[88:91], v[164:167], v[108:111]
	v_mfma_f32_16x16x32_bf16 v[28:31], v[104:107], v[164:167], v[28:31]
	v_mfma_f32_16x16x32_bf16 v[100:103], v[88:91], v[186:189], v[100:103]
	v_mfma_f32_16x16x32_bf16 v[20:23], v[104:107], v[186:189], v[20:23]
	v_mfma_f32_16x16x32_bf16 v[92:95], v[88:91], v[194:197], v[92:95]
	v_mfma_f32_16x16x32_bf16 v[12:15], v[104:107], v[194:197], v[12:15]
	v_mfma_f32_16x16x32_bf16 v[84:87], v[88:91], v[202:205], v[44:47]
	v_mfma_f32_16x16x32_bf16 v[4:7], v[104:107], v[202:205], v[4:7]
	s_setprio 0
	s_setprio 1
	v_mfma_f32_16x16x32_bf16 v[44:47], v[124:127], v[160:163], v[48:51]
	v_mfma_f32_16x16x32_bf16 v[104:107], v[128:131], v[164:167], v[44:47]
	v_mfma_f32_16x16x32_bf16 v[44:47], v[124:127], v[182:185], v[52:55]
	v_mfma_f32_16x16x32_bf16 v[96:99], v[128:131], v[186:189], v[44:47]
	v_mfma_f32_16x16x32_bf16 v[44:47], v[124:127], v[190:193], v[56:59]
	v_mfma_f32_16x16x32_bf16 v[24:27], v[132:135], v[160:163], v[24:27]
	v_mfma_f32_16x16x32_bf16 v[16:19], v[132:135], v[182:185], v[16:19]
	v_mfma_f32_16x16x32_bf16 v[88:91], v[128:131], v[194:197], v[44:47]
	v_mfma_f32_16x16x32_bf16 v[8:11], v[132:135], v[190:193], v[8:11]
	v_mfma_f32_16x16x32_bf16 v[44:47], v[124:127], v[198:201], v[80:83]
	v_mfma_f32_16x16x32_bf16 v[0:3], v[132:135], v[198:201], v[0:3]
	v_mfma_f32_16x16x32_bf16 v[24:27], v[136:139], v[164:167], v[24:27]
	v_mfma_f32_16x16x32_bf16 v[16:19], v[136:139], v[186:189], v[16:19]
	v_mfma_f32_16x16x32_bf16 v[8:11], v[136:139], v[194:197], v[8:11]
	v_mfma_f32_16x16x32_bf16 v[80:83], v[128:131], v[202:205], v[44:47]
	v_mfma_f32_16x16x32_bf16 v[0:3], v[136:139], v[202:205], v[0:3]
	s_setprio 0
	s_barrier
	s_add_i32 s45, s45, 2
	s_add_u32 s0, s0, 0x100
	s_addc_u32 s1, s1, 0
	s_add_u32 s43, s43, 0x100
	s_addc_u32 s44, s44, 0
	s_cmp_gt_u32 s45, 13
	s_cbranch_scc0 .LBB0_826
	s_and_b64 vcc, exec, s[18:19]
	s_cbranch_vccz .LBB0_829
	s_barrier

; #define PG8_STAGE(bufoff, gbase, voff) do { _Pragma("unroll") for (int _i = 0; _i < 2; ++_i) \
;         __builtin_amdgcn_global_load_lds((const unsigned*)((const char*)(gbase) + (voff)[_i]), (LAS unsigned*)(lds + (bufoff) + ldsw + _i * 8192), 16, 0, 0); } while (0)
; #define PG8_LDA(dst, b, h) do { _Pragma("unroll") for (int m = 0; m < 4; ++m) _Pragma("unroll") for (int k = 0; k < 2; ++k) dst[m][k] = *(const LAS bf16x8*)(lds + PG8_SA(b, h) + aoff + m * 2048 + k * 1024); } while (0)
; #define PG8_LDB(dst, b, h) do { _Pragma("unroll") for (int n = 0; n < 2; ++n) _Pragma("unroll") for (int k = 0; k < 2; ++k) dst[n][k] = *(const LAS bf16x8*)(lds + PG8_SB(b, h) + boff + n * 2048 + k * 1024); } while (0)
; #define PG8_MMA(ai, bj, At, Bt) do { __builtin_amdgcn_s_setprio(1); _Pragma("unroll") for (int m = 0; m < 4; ++m) _Pragma("unroll") for (int n = 0; n < 2; ++n) _Pragma("unroll") for (int k = 0; k < 2; ++k) \
;         acc[ai][bj][m][n] = __builtin_amdgcn_mfma_f32_16x16x32_bf16(Bt[n][k], At[m][k], acc[ai][bj][m][n], 0, 0, 0); __builtin_amdgcn_s_setprio(0); } while (0)
; #define PG8_WAIT_V(n) asm volatile("s_waitcnt vmcnt(" #n ")" ::: "memory")
; #define PG8_WAIT_L(n) asm volatile("s_waitcnt lgkmcnt(" #n ")" ::: "memory")
; #define PG8_BAR __builtin_amdgcn_s_barrier()
; #define PG8_SCHED __builtin_amdgcn_sched_barrier(0)
; template <class Epi, class Sched, bool ALIGN_EPI>
; DI void gemm_phase(LAS unsigned char* lds, const Gemm g, const Sched& S, const Epi& E) {
;     ...
;             PG8_LDB(B0, 0, 0); PG8_LDB(B1, 0, 1); PG8_SCHED; PG8_LDA(At, 0, 0); PG8_STAGE(PG8_SA(1, 1), a1 + hstep, voffA);
;             PG8_WAIT_V(8); PG8_WAIT_L(0); PG8_BAR; PG8_MMA(0, 0, At, B0); PG8_MMA(0, 1, At, B1); PG8_BAR; PG8_SCHED;
;             PG8_LDA(At, 0, 1); PG8_STAGE(PG8_SB(0, 0), b2, voffA); PG8_STAGE(PG8_SB(0, 1), b2 + hstep, voffA); PG8_STAGE(PG8_SA(0, 0), a2, voffA);
;             PG8_WAIT_V(8); PG8_WAIT_L(0); PG8_BAR; PG8_MMA(1, 0, At, B0); PG8_MMA(1, 1, At, B1); PG8_BAR; PG8_SCHED;
.LBB0_957:
	s_add_u32 s16, s0, 0xfffc0080
	s_addc_u32 s17, s1, -1
	s_add_i32 s43, 0, 0x10000
	s_cmp_eq_u32 s42, 12
	s_cselect_b32 s19, s5, s17
	s_cselect_b32 s18, s34, s16
	s_cselect_b32 s17, s15, s37
	s_cselect_b32 s16, s35, s36
	s_add_i32 s50, 0, 0x14000
	v_add_u32_e32 v144, s43, v133
	v_add_u32_e32 v160, s50, v133
	ds_read_b128 v[128:131], v144
	ds_read_b128 v[136:139], v144 offset:1024
	ds_read_b128 v[140:143], v144 offset:2048
	ds_read_b128 v[144:147], v144 offset:3072
	ds_read_b128 v[148:151], v160
	ds_read_b128 v[152:155], v160 offset:1024
	ds_read_b128 v[156:159], v160 offset:2048
	ds_read_b128 v[160:163], v160 offset:3072
	v_lshl_add_u64 v[210:211], s[0:1], 0, v[178:179]
	s_add_i32 m0, s22, 0xc000
	ds_read_b128 v[164:167], v135
	ds_read_b128 v[182:185], v135 offset:1024
	ds_read_b128 v[186:189], v135 offset:2048
	ds_read_b128 v[190:193], v135 offset:3072
	ds_read_b128 v[194:197], v135 offset:4096
	ds_read_b128 v[198:201], v135 offset:5120
	ds_read_b128 v[202:205], v135 offset:6144
	ds_read_b128 v[206:209], v135 offset:7168
	global_load_lds_dwordx4 v[210:211], off
	v_lshl_add_u64 v[210:211], s[0:1], 0, v[180:181]
	s_add_i32 m0, s22, 0xe000
	s_nop 0
	global_load_lds_dwordx4 v[210:211], off
	s_waitcnt vmcnt(8)
	s_waitcnt lgkmcnt(0)
	s_barrier
	s_setprio 1
	s_waitcnt lgkmcnt(0)
	v_mfma_f32_16x16x32_bf16 v[124:127], v[128:131], v[164:167], v[124:127]
	v_mfma_f32_16x16x32_bf16 v[120:123], v[140:143], v[164:167], v[120:123]
	v_mfma_f32_16x16x32_bf16 v[108:111], v[128:131], v[186:189], v[108:111]
	v_mfma_f32_16x16x32_bf16 v[104:107], v[140:143], v[186:189], v[104:107]
	v_mfma_f32_16x16x32_bf16 v[92:95], v[128:131], v[194:197], v[92:95]
	v_mfma_f32_16x16x32_bf16 v[88:91], v[140:143], v[194:197], v[88:91]
	v_mfma_f32_16x16x32_bf16 v[76:79], v[128:131], v[202:205], v[76:79]
	v_mfma_f32_16x16x32_bf16 v[72:75], v[140:143], v[202:205], v[72:75]
	v_mfma_f32_16x16x32_bf16 v[124:127], v[136:139], v[182:185], v[124:127]
	v_mfma_f32_16x16x32_bf16 v[120:123], v[144:147], v[182:185], v[120:123]
	v_mfma_f32_16x16x32_bf16 v[108:111], v[136:139], v[190:193], v[108:111]
	v_mfma_f32_16x16x32_bf16 v[104:107], v[144:147], v[190:193], v[104:107]
	v_mfma_f32_16x16x32_bf16 v[92:95], v[136:139], v[198:201], v[92:95]
	v_mfma_f32_16x16x32_bf16 v[88:91], v[144:147], v[198:201], v[88:91]
	v_mfma_f32_16x16x32_bf16 v[76:79], v[136:139], v[206:209], v[76:79]
	v_mfma_f32_16x16x32_bf16 v[72:75], v[144:147], v[206:209], v[72:75]
	s_setprio 0
	s_setprio 1
	v_mfma_f32_16x16x32_bf16 v[116:119], v[148:151], v[164:167], v[116:119]
	v_mfma_f32_16x16x32_bf16 v[112:115], v[156:159], v[164:167], v[112:115]
	v_mfma_f32_16x16x32_bf16 v[100:103], v[148:151], v[186:189], v[100:103]
	v_mfma_f32_16x16x32_bf16 v[96:99], v[156:159], v[186:189], v[96:99]
	v_mfma_f32_16x16x32_bf16 v[84:87], v[148:151], v[194:197], v[84:87]
	v_mfma_f32_16x16x32_bf16 v[80:83], v[156:159], v[194:197], v[80:83]
	v_mfma_f32_16x16x32_bf16 v[68:71], v[148:151], v[202:205], v[68:71]
	v_mfma_f32_16x16x32_bf16 v[64:67], v[156:159], v[202:205], v[64:67]
	v_mfma_f32_16x16x32_bf16 v[116:119], v[152:155], v[182:185], v[116:119]
	v_mfma_f32_16x16x32_bf16 v[112:115], v[160:163], v[182:185], v[112:115]
	v_mfma_f32_16x16x32_bf16 v[100:103], v[152:155], v[190:193], v[100:103]
	v_mfma_f32_16x16x32_bf16 v[96:99], v[160:163], v[190:193], v[96:99]
	v_mfma_f32_16x16x32_bf16 v[84:87], v[152:155], v[198:201], v[84:87]
	v_mfma_f32_16x16x32_bf16 v[80:83], v[160:163], v[198:201], v[80:83]
	v_mfma_f32_16x16x32_bf16 v[68:71], v[152:155], v[206:209], v[68:71]
	v_mfma_f32_16x16x32_bf16 v[64:67], v[160:163], v[206:209], v[64:67]
	s_setprio 0
	s_barrier
	s_add_i32 s43, s43, s20
	v_lshl_add_u64 v[210:211], s[16:17], 0, v[174:175]
	s_mov_b32 m0, s43
	ds_read_b128 v[164:167], v135 offset:16384
	ds_read_b128 v[182:185], v135 offset:17408
	ds_read_b128 v[186:189], v135 offset:18432
	ds_read_b128 v[190:193], v135 offset:19456
	ds_read_b128 v[194:197], v135 offset:20480
	ds_read_b128 v[198:201], v135 offset:21504
	ds_read_b128 v[202:205], v135 offset:22528
	ds_read_b128 v[206:209], v135 offset:23552
	global_load_lds_dwordx4 v[210:211], off
	s_add_i32 m0, s43, 0x2000
	s_add_u32 s48, s16, 0x40000
	v_lshl_add_u64 v[212:213], s[16:17], 0, v[176:177]
	s_addc_u32 s49, s17, 0
	s_add_i32 s43, s50, s20
	global_load_lds_dwordx4 v[212:213], off
	v_lshl_add_u64 v[214:215], s[48:49], 0, v[174:175]
	s_mov_b32 m0, s43
	v_lshl_add_u64 v[216:217], s[18:19], 0, v[176:177]
	global_load_lds_dwordx4 v[214:215], off
	v_lshl_add_u64 v[214:215], s[48:49], 0, v[176:177]
	s_add_i32 m0, s43, 0x2000
	s_nop 0
	global_load_lds_dwordx4 v[214:215], off
	s_waitcnt vmcnt(6)
	s_waitcnt lgkmcnt(0)
	s_barrier
; #define PG8_STAGE(bufoff, gbase, voff) do { _Pragma("unroll") for (int _i = 0; _i < 2; ++_i) \
;         __builtin_amdgcn_global_load_lds((const unsigned*)((const char*)(gbase) + (voff)[_i]), (LAS unsigned*)(lds + (bufoff) + ldsw + _i * 8192), 16, 0, 0); } while (0)
; #define PG8_LDA(dst, b, h) do { _Pragma("unroll") for (int m = 0; m < 4; ++m) _Pragma("unroll") for (int k = 0; k < 2; ++k) dst[m][k] = *(const LAS bf16x8*)(lds + PG8_SA(b, h) + aoff + m * 2048 + k * 1024); } while (0)
; #define PG8_LDB(dst, b, h) do { _Pragma("unroll") for (int n = 0; n < 2; ++n) _Pragma("unroll") for (int k = 0; k < 2; ++k) dst[n][k] = *(const LAS bf16x8*)(lds + PG8_SB(b, h) + boff + n * 2048 + k * 1024); } while (0)
; #define PG8_MMA(ai, bj, At, Bt) do { __builtin_amdgcn_s_setprio(1); _Pragma("unroll") for (int m = 0; m < 4; ++m) _Pragma("unroll") for (int n = 0; n < 2; ++n) _Pragma("unroll") for (int k = 0; k < 2; ++k) \
;         acc[ai][bj][m][n] = __builtin_amdgcn_mfma_f32_16x16x32_bf16(Bt[n][k], At[m][k], acc[ai][bj][m][n], 0, 0, 0); __builtin_amdgcn_s_setprio(0); } while (0)
; #define PG8_WAIT_V(n) asm volatile("s_waitcnt vmcnt(" #n ")" ::: "memory")
; #define PG8_WAIT_L(n) asm volatile("s_waitcnt lgkmcnt(" #n ")" ::: "memory")
; #define PG8_BAR __builtin_amdgcn_s_barrier()
; #define PG8_SCHED __builtin_amdgcn_sched_barrier(0)
; template <class Epi, class Sched, bool ALIGN_EPI>
; DI void gemm_phase(LAS unsigned char* lds, const Gemm g, const Sched& S, const Epi& E) {
;     ...
;             PG8_WAIT_V(8); PG8_WAIT_L(0); PG8_BAR; PG8_MMA(1, 0, At, B0); PG8_MMA(1, 1, At, B1); PG8_BAR; PG8_SCHED;
;             PG8_LDB(B0, 1, 0); PG8_LDB(B1, 1, 1); PG8_SCHED; PG8_LDA(At, 1, 0); PG8_STAGE(PG8_SA(0, 1), a2 + hstep, voffA);
;             PG8_WAIT_V(8); PG8_WAIT_L(0); PG8_BAR; PG8_MMA(0, 0, At, B0); PG8_MMA(0, 1, At, B1); PG8_BAR; PG8_SCHED;
	s_setprio 1
	s_waitcnt lgkmcnt(0)
	v_mfma_f32_16x16x32_bf16 v[60:63], v[128:131], v[164:167], v[60:63]
	v_mfma_f32_16x16x32_bf16 v[56:59], v[140:143], v[164:167], v[56:59]
	v_mfma_f32_16x16x32_bf16 v[44:47], v[128:131], v[186:189], v[44:47]
	v_mfma_f32_16x16x32_bf16 v[40:43], v[140:143], v[186:189], v[40:43]
	v_mfma_f32_16x16x32_bf16 v[28:31], v[128:131], v[194:197], v[28:31]
	v_mfma_f32_16x16x32_bf16 v[24:27], v[140:143], v[194:197], v[24:27]
	v_mfma_f32_16x16x32_bf16 v[12:15], v[128:131], v[202:205], v[12:15]
	v_mfma_f32_16x16x32_bf16 v[8:11], v[140:143], v[202:205], v[8:11]
	v_mfma_f32_16x16x32_bf16 v[60:63], v[136:139], v[182:185], v[60:63]
	v_mfma_f32_16x16x32_bf16 v[56:59], v[144:147], v[182:185], v[56:59]
	v_mfma_f32_16x16x32_bf16 v[44:47], v[136:139], v[190:193], v[44:47]
	v_mfma_f32_16x16x32_bf16 v[40:43], v[144:147], v[190:193], v[40:43]
	v_mfma_f32_16x16x32_bf16 v[28:31], v[136:139], v[198:201], v[28:31]
	v_mfma_f32_16x16x32_bf16 v[24:27], v[144:147], v[198:201], v[24:27]
	v_mfma_f32_16x16x32_bf16 v[12:15], v[136:139], v[206:209], v[12:15]
	v_mfma_f32_16x16x32_bf16 v[8:11], v[144:147], v[206:209], v[8:11]
	s_setprio 0
	s_setprio 1
	v_mfma_f32_16x16x32_bf16 v[52:55], v[148:151], v[164:167], v[52:55]
	v_mfma_f32_16x16x32_bf16 v[48:51], v[156:159], v[164:167], v[48:51]
	v_mfma_f32_16x16x32_bf16 v[36:39], v[148:151], v[186:189], v[36:39]
	v_mfma_f32_16x16x32_bf16 v[32:35], v[156:159], v[186:189], v[32:35]
	v_mfma_f32_16x16x32_bf16 v[20:23], v[148:151], v[194:197], v[20:23]
	v_mfma_f32_16x16x32_bf16 v[16:19], v[156:159], v[194:197], v[16:19]
	v_mfma_f32_16x16x32_bf16 v[4:7], v[148:151], v[202:205], v[4:7]
	v_mfma_f32_16x16x32_bf16 v[0:3], v[156:159], v[202:205], v[0:3]
	v_mfma_f32_16x16x32_bf16 v[52:55], v[152:155], v[182:185], v[52:55]
	v_mfma_f32_16x16x32_bf16 v[48:51], v[160:163], v[182:185], v[48:51]
	v_mfma_f32_16x16x32_bf16 v[36:39], v[152:155], v[190:193], v[36:39]
	v_mfma_f32_16x16x32_bf16 v[32:35], v[160:163], v[190:193], v[32:35]
	v_mfma_f32_16x16x32_bf16 v[20:23], v[152:155], v[198:201], v[20:23]
	v_mfma_f32_16x16x32_bf16 v[16:19], v[160:163], v[198:201], v[16:19]
	v_mfma_f32_16x16x32_bf16 v[4:7], v[152:155], v[206:209], v[4:7]
	v_mfma_f32_16x16x32_bf16 v[0:3], v[160:163], v[206:209], v[0:3]
	s_setprio 0
	s_barrier
	s_add_i32 s43, 0, 0x18000
	s_add_i32 s48, 0, 0x1c000
	v_add_u32_e32 v144, s43, v133
	v_add_u32_e32 v160, s48, v133
	ds_read_b128 v[128:131], v144
	ds_read_b128 v[136:139], v144 offset:1024
	ds_read_b128 v[140:143], v144 offset:2048
	ds_read_b128 v[144:147], v144 offset:3072
	ds_read_b128 v[148:151], v160
	ds_read_b128 v[152:155], v160 offset:1024
	ds_read_b128 v[156:159], v160 offset:2048
	ds_read_b128 v[160:163], v160 offset:3072
	v_lshl_add_u64 v[214:215], s[18:19], 0, v[174:175]
	s_mov_b32 m0, s22
	s_nop 0
	global_load_lds_dwordx4 v[214:215], off
	s_mov_b32 m0, s23
	s_nop 0
	global_load_lds_dwordx4 v[216:217], off
	s_add_u32 s18, s18, 0x40000
	s_addc_u32 s19, s19, 0
	s_mov_b32 m0, s24
	v_lshl_add_u64 v[218:219], s[18:19], 0, v[174:175]
	ds_read_b128 v[164:167], v135 offset:32768
	ds_read_b128 v[182:185], v135 offset:33792
	ds_read_b128 v[186:189], v135 offset:34816
	ds_read_b128 v[190:193], v135 offset:35840
	ds_read_b128 v[194:197], v135 offset:36864
	ds_read_b128 v[198:201], v135 offset:37888
	ds_read_b128 v[202:205], v135 offset:38912
	ds_read_b128 v[206:209], v135 offset:39936
	global_load_lds_dwordx4 v[218:219], off
	v_lshl_add_u64 v[218:219], s[18:19], 0, v[176:177]
	s_mov_b32 m0, s25
	s_nop 0
	global_load_lds_dwordx4 v[218:219], off
	s_waitcnt vmcnt(8)
	s_waitcnt lgkmcnt(0)
	s_barrier
	s_setprio 1
	s_waitcnt lgkmcnt(0)
	v_mfma_f32_16x16x32_bf16 v[124:127], v[128:131], v[164:167], v[124:127]
	v_mfma_f32_16x16x32_bf16 v[120:123], v[140:143], v[164:167], v[120:123]
	v_mfma_f32_16x16x32_bf16 v[108:111], v[128:131], v[186:189], v[108:111]
	v_mfma_f32_16x16x32_bf16 v[104:107], v[140:143], v[186:189], v[104:107]
	v_mfma_f32_16x16x32_bf16 v[92:95], v[128:131], v[194:197], v[92:95]
	v_mfma_f32_16x16x32_bf16 v[88:91], v[140:143], v[194:197], v[88:91]
	v_mfma_f32_16x16x32_bf16 v[76:79], v[128:131], v[202:205], v[76:79]
	v_mfma_f32_16x16x32_bf16 v[72:75], v[140:143], v[202:205], v[72:75]
	v_mfma_f32_16x16x32_bf16 v[124:127], v[136:139], v[182:185], v[124:127]
	v_mfma_f32_16x16x32_bf16 v[120:123], v[144:147], v[182:185], v[120:123]
	v_mfma_f32_16x16x32_bf16 v[108:111], v[136:139], v[190:193], v[108:111]
	v_mfma_f32_16x16x32_bf16 v[104:107], v[144:147], v[190:193], v[104:107]
	v_mfma_f32_16x16x32_bf16 v[92:95], v[136:139], v[198:201], v[92:95]
	v_mfma_f32_16x16x32_bf16 v[88:91], v[144:147], v[198:201], v[88:91]
	v_mfma_f32_16x16x32_bf16 v[76:79], v[136:139], v[206:209], v[76:79]
	v_mfma_f32_16x16x32_bf16 v[72:75], v[144:147], v[206:209], v[72:75]
	s_setprio 0
	s_setprio 1
	v_mfma_f32_16x16x32_bf16 v[116:119], v[148:151], v[164:167], v[116:119]
	v_mfma_f32_16x16x32_bf16 v[112:115], v[156:159], v[164:167], v[112:115]
	v_mfma_f32_16x16x32_bf16 v[100:103], v[148:151], v[186:189], v[100:103]
	v_mfma_f32_16x16x32_bf16 v[96:99], v[156:159], v[186:189], v[96:99]
	v_mfma_f32_16x16x32_bf16 v[84:87], v[148:151], v[194:197], v[84:87]
	v_mfma_f32_16x16x32_bf16 v[80:83], v[156:159], v[194:197], v[80:83]
	v_mfma_f32_16x16x32_bf16 v[68:71], v[148:151], v[202:205], v[68:71]
	v_mfma_f32_16x16x32_bf16 v[64:67], v[156:159], v[202:205], v[64:67]
	v_mfma_f32_16x16x32_bf16 v[116:119], v[152:155], v[182:185], v[116:119]
	v_mfma_f32_16x16x32_bf16 v[112:115], v[160:163], v[182:185], v[112:115]
	v_mfma_f32_16x16x32_bf16 v[100:103], v[152:155], v[190:193], v[100:103]
	v_mfma_f32_16x16x32_bf16 v[96:99], v[160:163], v[190:193], v[96:99]
	v_mfma_f32_16x16x32_bf16 v[84:87], v[152:155], v[198:201], v[84:87]
	v_mfma_f32_16x16x32_bf16 v[80:83], v[160:163], v[198:201], v[80:83]
	v_mfma_f32_16x16x32_bf16 v[68:71], v[152:155], v[206:209], v[68:71]
	v_mfma_f32_16x16x32_bf16 v[64:67], v[160:163], v[206:209], v[64:67]
	s_setprio 0
	s_barrier
; #define PG8_STAGE(bufoff, gbase, voff) do { _Pragma("unroll") for (int _i = 0; _i < 2; ++_i) \
;         __builtin_amdgcn_global_load_lds((const unsigned*)((const char*)(gbase) + (voff)[_i]), (LAS unsigned*)(lds + (bufoff) + ldsw + _i * 8192), 16, 0, 0); } while (0)
; #define PG8_LDA(dst, b, h) do { _Pragma("unroll") for (int m = 0; m < 4; ++m) _Pragma("unroll") for (int k = 0; k < 2; ++k) dst[m][k] = *(const LAS bf16x8*)(lds + PG8_SA(b, h) + aoff + m * 2048 + k * 1024); } while (0)
; #define PG8_MMA(ai, bj, At, Bt) do { __builtin_amdgcn_s_setprio(1); _Pragma("unroll") for (int m = 0; m < 4; ++m) _Pragma("unroll") for (int n = 0; n < 2; ++n) _Pragma("unroll") for (int k = 0; k < 2; ++k) \
;         acc[ai][bj][m][n] = __builtin_amdgcn_mfma_f32_16x16x32_bf16(Bt[n][k], At[m][k], acc[ai][bj][m][n], 0, 0, 0); __builtin_amdgcn_s_setprio(0); } while (0)
; #define PG8_WAIT_V(n) asm volatile("s_waitcnt vmcnt(" #n ")" ::: "memory")
; #define PG8_WAIT_L(n) asm volatile("s_waitcnt lgkmcnt(" #n ")" ::: "memory")
; #define PG8_BAR __builtin_amdgcn_s_barrier()
; #define PG8_SCHED __builtin_amdgcn_sched_barrier(0)
; template <class Epi, class Sched, bool ALIGN_EPI>
; DI void gemm_phase(LAS unsigned char* lds, const Gemm g, const Sched& S, const Epi& E) {
;     ...
;             PG8_LDA(At, 1, 1); PG8_STAGE(PG8_SB(1, 0), b3, voffA); PG8_STAGE(PG8_SB(1, 1), b3 + hstep, voffA); PG8_STAGE(PG8_SA(1, 0), a3, voffA);
;             PG8_WAIT_V(8); PG8_WAIT_L(0); PG8_BAR; PG8_MMA(1, 0, At, B0); PG8_MMA(1, 1, At, B1); PG8_BAR; PG8_SCHED;
;         }
	s_add_i32 s18, s43, s20
	v_lshl_add_u64 v[210:211], v[210:211], 0, s[2:3]
	s_mov_b32 m0, s18
	ds_read_b128 v[164:167], v135 offset:49152
	ds_read_b128 v[182:185], v135 offset:50176
	ds_read_b128 v[186:189], v135 offset:51200
	ds_read_b128 v[190:193], v135 offset:52224
	ds_read_b128 v[194:197], v135 offset:53248
	ds_read_b128 v[198:201], v135 offset:54272
	ds_read_b128 v[202:205], v135 offset:55296
	ds_read_b128 v[206:209], v135 offset:56320
	global_load_lds_dwordx4 v[210:211], off
	s_add_i32 m0, s18, 0x2000
	s_add_u32 s16, s16, 0x40080
	v_lshl_add_u64 v[210:211], v[212:213], 0, s[2:3]
	s_addc_u32 s17, s17, 0
	s_add_i32 s18, s48, s20
	global_load_lds_dwordx4 v[210:211], off
	v_lshl_add_u64 v[210:211], s[16:17], 0, v[174:175]
	s_mov_b32 m0, s18
	s_nop 0
	global_load_lds_dwordx4 v[210:211], off
	v_lshl_add_u64 v[210:211], s[16:17], 0, v[176:177]
	s_add_i32 m0, s18, 0x2000
	s_nop 0
	global_load_lds_dwordx4 v[210:211], off
	v_lshl_add_u64 v[210:211], v[214:215], 0, s[2:3]
	s_mov_b32 m0, s26
	s_nop 0
	global_load_lds_dwordx4 v[210:211], off
	v_lshl_add_u64 v[210:211], v[216:217], 0, s[2:3]
	s_mov_b32 m0, s27
	s_nop 0
	global_load_lds_dwordx4 v[210:211], off
	s_waitcnt vmcnt(8)
	s_waitcnt lgkmcnt(0)
	s_barrier
	s_setprio 1
	s_waitcnt lgkmcnt(0)
	v_mfma_f32_16x16x32_bf16 v[60:63], v[128:131], v[164:167], v[60:63]
	v_mfma_f32_16x16x32_bf16 v[56:59], v[140:143], v[164:167], v[56:59]
	v_mfma_f32_16x16x32_bf16 v[44:47], v[128:131], v[186:189], v[44:47]
	v_mfma_f32_16x16x32_bf16 v[40:43], v[140:143], v[186:189], v[40:43]
	v_mfma_f32_16x16x32_bf16 v[28:31], v[128:131], v[194:197], v[28:31]
	v_mfma_f32_16x16x32_bf16 v[24:27], v[140:143], v[194:197], v[24:27]
	v_mfma_f32_16x16x32_bf16 v[12:15], v[128:131], v[202:205], v[12:15]
	v_mfma_f32_16x16x32_bf16 v[8:11], v[140:143], v[202:205], v[8:11]
	v_mfma_f32_16x16x32_bf16 v[60:63], v[136:139], v[182:185], v[60:63]
	v_mfma_f32_16x16x32_bf16 v[56:59], v[144:147], v[182:185], v[56:59]
	v_mfma_f32_16x16x32_bf16 v[44:47], v[136:139], v[190:193], v[44:47]
	v_mfma_f32_16x16x32_bf16 v[40:43], v[144:147], v[190:193], v[40:43]
	v_mfma_f32_16x16x32_bf16 v[28:31], v[136:139], v[198:201], v[28:31]
	v_mfma_f32_16x16x32_bf16 v[24:27], v[144:147], v[198:201], v[24:27]
	v_mfma_f32_16x16x32_bf16 v[12:15], v[136:139], v[206:209], v[12:15]
	v_mfma_f32_16x16x32_bf16 v[8:11], v[144:147], v[206:209], v[8:11]
	s_setprio 0
	s_setprio 1
	v_mfma_f32_16x16x32_bf16 v[52:55], v[148:151], v[164:167], v[52:55]
	v_mfma_f32_16x16x32_bf16 v[48:51], v[156:159], v[164:167], v[48:51]
	v_mfma_f32_16x16x32_bf16 v[36:39], v[148:151], v[186:189], v[36:39]
	v_mfma_f32_16x16x32_bf16 v[32:35], v[156:159], v[186:189], v[32:35]
	v_mfma_f32_16x16x32_bf16 v[20:23], v[148:151], v[194:197], v[20:23]
	v_mfma_f32_16x16x32_bf16 v[16:19], v[156:159], v[194:197], v[16:19]
	v_mfma_f32_16x16x32_bf16 v[4:7], v[148:151], v[202:205], v[4:7]
	v_mfma_f32_16x16x32_bf16 v[0:3], v[156:159], v[202:205], v[0:3]
	v_mfma_f32_16x16x32_bf16 v[52:55], v[152:155], v[182:185], v[52:55]
	v_mfma_f32_16x16x32_bf16 v[48:51], v[160:163], v[182:185], v[48:51]
	v_mfma_f32_16x16x32_bf16 v[36:39], v[152:155], v[190:193], v[36:39]
	v_mfma_f32_16x16x32_bf16 v[32:35], v[160:163], v[190:193], v[32:35]
	v_mfma_f32_16x16x32_bf16 v[20:23], v[152:155], v[198:201], v[20:23]
	v_mfma_f32_16x16x32_bf16 v[16:19], v[160:163], v[198:201], v[16:19]
	v_mfma_f32_16x16x32_bf16 v[4:7], v[152:155], v[206:209], v[4:7]
	v_mfma_f32_16x16x32_bf16 v[0:3], v[160:163], v[206:209], v[0:3]
	s_setprio 0
	s_barrier
	s_add_i32 s42, s42, 2
	s_add_u32 s0, s0, 0x100
	s_addc_u32 s1, s1, 0
	s_add_u32 s36, s36, 0x100
	s_addc_u32 s37, s37, 0
	s_cmp_gt_u32 s42, 13
	s_cbranch_scc0 .LBB0_957
	s_and_b64 vcc, exec, s[12:13]
	s_cbranch_vccz .LBB0_960
	s_barrier
